# cache-policy hints: nt on rms row loads, mlp1 output stores and gate-GEMM output stores
# baseline (speedup 1.0000x reference)
.LBB0_275:
	s_ashr_i32 s14, s36, 2
	s_ashr_i32 s15, s14, 31
	s_lshl_b64 s[16:17], s[14:15], 27
	s_add_u32 s1, s27, s16
	s_addc_u32 s9, s28, s17
	s_cmp_lt_i32 s14, 2
	v_mul_f32_e32 v120, 0xbfb8aa3b, v120
	s_cselect_b32 s9, s9, s30
	s_cselect_b32 s1, s1, s29
	s_lshl_b32 s14, s36, 9
	v_exp_f32_e32 v120, v120
	v_mul_f32_e32 v121, 0xbfb8aa3b, v121
	s_and_b32 s14, s14, 0x600
	v_exp_f32_e32 v121, v121
	v_lshl_add_u32 v142, s37, 8, v144
	s_add_u32 s14, s1, s14
	s_addc_u32 s15, s9, 0
	v_ashrrev_i32_e32 v143, 31, v142
	v_mul_f32_e32 v124, 0xbfb8aa3b, v124
	v_lshl_add_u64 v[140:141], v[134:135], 1, s[14:15]
	v_lshlrev_b64 v[148:149], 11, v[142:143]
	v_exp_f32_e32 v143, v124
	v_mul_f32_e32 v124, 0xbfb8aa3b, v125
	v_add_f32_e32 v120, 1.0, v120
	v_exp_f32_e32 v147, v124
	v_lshl_add_u64 v[124:125], v[140:141], 0, v[148:149]
	v_rcp_f32_e32 v148, v120
	v_add_f32_e32 v120, 1.0, v121
	v_mul_f32_e32 v121, 0xbfb8aa3b, v122
	v_mul_f32_e32 v126, 0xbfb8aa3b, v126
	v_mul_f32_e32 v127, 0xbfb8aa3b, v127
	v_exp_f32_e32 v121, v121
	v_mul_f32_e32 v122, 0xbfb8aa3b, v123
	v_exp_f32_e32 v126, v126
	v_exp_f32_e32 v127, v127
	v_exp_f32_e32 v122, v122
	v_rcp_f32_e32 v123, v120
	v_add_f32_e32 v120, 1.0, v121
	v_add_f32_e32 v143, 1.0, v143
	v_add_f32_e32 v147, 1.0, v147
	v_add_f32_e32 v126, 1.0, v126
	v_add_f32_e32 v127, 1.0, v127
	v_rcp_f32_e32 v149, v120
	v_add_f32_e32 v120, 1.0, v122
	v_mul_f32_e32 v112, 0xbfb8aa3b, v112
	v_rcp_f32_e32 v143, v143
	v_rcp_f32_e32 v147, v147
	v_rcp_f32_e32 v126, v126
	v_rcp_f32_e32 v127, v127
	v_rcp_f32_e32 v150, v120
	v_exp_f32_e32 v112, v112
	v_mul_f32_e32 v113, 0xbfb8aa3b, v113
	v_exp_f32_e32 v113, v113
	v_cvt_pk_bf16_f32 v120, v143, v147
	v_cvt_pk_bf16_f32 v121, v126, v127
	v_cvt_pk_bf16_f32 v122, v148, v123
	v_cvt_pk_bf16_f32 v123, v149, v150
	v_add_f32_e32 v112, 1.0, v112
	global_store_dwordx4 v[124:125], v[120:123], off nt
	v_mul_f32_e32 v116, 0xbfb8aa3b, v116
	v_mul_f32_e32 v117, 0xbfb8aa3b, v117
	v_rcp_f32_e32 v120, v112
	v_add_f32_e32 v112, 1.0, v113
	v_mul_f32_e32 v113, 0xbfb8aa3b, v114
	v_mul_f32_e32 v118, 0xbfb8aa3b, v118
	v_mul_f32_e32 v119, 0xbfb8aa3b, v119
	v_exp_f32_e32 v113, v113
	v_mul_f32_e32 v114, 0xbfb8aa3b, v115
	v_exp_f32_e32 v116, v116
	v_exp_f32_e32 v117, v117
	v_exp_f32_e32 v118, v118
	v_exp_f32_e32 v119, v119
	v_exp_f32_e32 v114, v114
	v_rcp_f32_e32 v115, v112
	v_add_f32_e32 v112, 1.0, v113
	v_add_f32_e32 v116, 1.0, v116
	v_add_f32_e32 v117, 1.0, v117
	v_add_f32_e32 v118, 1.0, v118
	v_add_f32_e32 v119, 1.0, v119
	v_rcp_f32_e32 v121, v112
	v_add_f32_e32 v112, 1.0, v114
	v_rcp_f32_e32 v116, v116
	v_rcp_f32_e32 v117, v117
	v_rcp_f32_e32 v118, v118
	v_rcp_f32_e32 v119, v119
	v_rcp_f32_e32 v122, v112
	v_mul_f32_e32 v104, 0xbfb8aa3b, v104
	v_cvt_pk_bf16_f32 v112, v116, v117
	v_cvt_pk_bf16_f32 v113, v118, v119
	v_cvt_pk_bf16_f32 v114, v120, v115
	v_cvt_pk_bf16_f32 v115, v121, v122
	v_mul_f32_e32 v108, 0xbfb8aa3b, v108
	v_exp_f32_e32 v104, v104
	v_mul_f32_e32 v105, 0xbfb8aa3b, v105
	global_store_dwordx4 v[124:125], v[112:115], off offset:256 nt
	v_exp_f32_e32 v105, v105
	v_add_f32_e32 v104, 1.0, v104
	v_exp_f32_e32 v114, v108
	v_or_b32_e32 v112, 16, v142
	v_ashrrev_i32_e32 v113, 31, v112
	v_lshlrev_b64 v[112:113], 11, v[112:113]
	v_mul_f32_e32 v108, 0xbfb8aa3b, v109
	v_exp_f32_e32 v115, v108
	v_lshl_add_u64 v[108:109], v[140:141], 0, v[112:113]
	v_add_f32_e32 v112, 1.0, v114
	v_rcp_f32_e32 v114, v104
	v_add_f32_e32 v104, 1.0, v105
	v_mul_f32_e32 v105, 0xbfb8aa3b, v106
	v_mul_f32_e32 v110, 0xbfb8aa3b, v110
	v_mul_f32_e32 v111, 0xbfb8aa3b, v111
	v_exp_f32_e32 v105, v105
	v_mul_f32_e32 v106, 0xbfb8aa3b, v107
	v_exp_f32_e32 v110, v110
	v_exp_f32_e32 v111, v111
	v_exp_f32_e32 v106, v106
	v_rcp_f32_e32 v107, v104
	v_add_f32_e32 v104, 1.0, v105
	v_add_f32_e32 v113, 1.0, v115
	v_add_f32_e32 v110, 1.0, v110
	v_add_f32_e32 v111, 1.0, v111
	v_rcp_f32_e32 v115, v104
	v_add_f32_e32 v104, 1.0, v106
	v_mul_f32_e32 v96, 0xbfb8aa3b, v96
	v_rcp_f32_e32 v112, v112
	v_rcp_f32_e32 v113, v113
	v_rcp_f32_e32 v110, v110
	v_rcp_f32_e32 v111, v111
	v_rcp_f32_e32 v116, v104
	v_exp_f32_e32 v96, v96
	v_mul_f32_e32 v97, 0xbfb8aa3b, v97
	v_exp_f32_e32 v97, v97
	v_cvt_pk_bf16_f32 v104, v112, v113
	v_cvt_pk_bf16_f32 v105, v110, v111
	v_cvt_pk_bf16_f32 v106, v114, v107
	v_cvt_pk_bf16_f32 v107, v115, v116
	v_add_f32_e32 v96, 1.0, v96
	global_store_dwordx4 v[108:109], v[104:107], off nt
	v_mul_f32_e32 v100, 0xbfb8aa3b, v100
	v_mul_f32_e32 v101, 0xbfb8aa3b, v101
	v_rcp_f32_e32 v104, v96
	v_add_f32_e32 v96, 1.0, v97
	v_mul_f32_e32 v97, 0xbfb8aa3b, v98
	v_mul_f32_e32 v102, 0xbfb8aa3b, v102
	v_mul_f32_e32 v103, 0xbfb8aa3b, v103
	v_exp_f32_e32 v97, v97
	v_mul_f32_e32 v98, 0xbfb8aa3b, v99
	v_exp_f32_e32 v100, v100
	v_exp_f32_e32 v101, v101
	v_exp_f32_e32 v102, v102
	v_exp_f32_e32 v103, v103
	v_exp_f32_e32 v98, v98
	v_rcp_f32_e32 v99, v96
	v_add_f32_e32 v96, 1.0, v97
	v_add_f32_e32 v100, 1.0, v100
	v_add_f32_e32 v101, 1.0, v101
	v_add_f32_e32 v102, 1.0, v102
	v_add_f32_e32 v103, 1.0, v103
	v_rcp_f32_e32 v105, v96
	v_add_f32_e32 v96, 1.0, v98
	v_rcp_f32_e32 v100, v100
	v_rcp_f32_e32 v101, v101
	v_rcp_f32_e32 v102, v102
	v_rcp_f32_e32 v103, v103
	v_rcp_f32_e32 v106, v96
	v_mul_f32_e32 v88, 0xbfb8aa3b, v88
	v_cvt_pk_bf16_f32 v96, v100, v101
	v_cvt_pk_bf16_f32 v97, v102, v103
	v_cvt_pk_bf16_f32 v98, v104, v99
	v_cvt_pk_bf16_f32 v99, v105, v106
	v_mul_f32_e32 v92, 0xbfb8aa3b, v92
	v_exp_f32_e32 v88, v88
	v_mul_f32_e32 v89, 0xbfb8aa3b, v89
	global_store_dwordx4 v[108:109], v[96:99], off offset:256 nt
	v_exp_f32_e32 v89, v89
	v_add_f32_e32 v88, 1.0, v88
	v_exp_f32_e32 v98, v92
	v_or_b32_e32 v96, 32, v142
	v_ashrrev_i32_e32 v97, 31, v96
	v_lshlrev_b64 v[96:97], 11, v[96:97]
	v_mul_f32_e32 v92, 0xbfb8aa3b, v93
	v_exp_f32_e32 v99, v92
	v_lshl_add_u64 v[92:93], v[140:141], 0, v[96:97]
	v_add_f32_e32 v96, 1.0, v98
	v_rcp_f32_e32 v98, v88
	v_add_f32_e32 v88, 1.0, v89
	v_mul_f32_e32 v89, 0xbfb8aa3b, v90
	v_mul_f32_e32 v94, 0xbfb8aa3b, v94
	v_mul_f32_e32 v95, 0xbfb8aa3b, v95
	v_exp_f32_e32 v89, v89
	v_mul_f32_e32 v90, 0xbfb8aa3b, v91
	v_exp_f32_e32 v94, v94
	v_exp_f32_e32 v95, v95
	v_exp_f32_e32 v90, v90
	v_rcp_f32_e32 v91, v88
	v_add_f32_e32 v88, 1.0, v89
	v_add_f32_e32 v97, 1.0, v99
	v_add_f32_e32 v94, 1.0, v94
	v_add_f32_e32 v95, 1.0, v95
	v_rcp_f32_e32 v99, v88
	v_add_f32_e32 v88, 1.0, v90
	v_mul_f32_e32 v80, 0xbfb8aa3b, v80
	v_rcp_f32_e32 v96, v96
	v_rcp_f32_e32 v97, v97
	v_rcp_f32_e32 v94, v94
	v_rcp_f32_e32 v95, v95
	v_rcp_f32_e32 v100, v88
	v_exp_f32_e32 v80, v80
	v_mul_f32_e32 v81, 0xbfb8aa3b, v81
	v_exp_f32_e32 v81, v81
	v_cvt_pk_bf16_f32 v88, v96, v97
	v_cvt_pk_bf16_f32 v89, v94, v95
	v_cvt_pk_bf16_f32 v90, v98, v91
	v_cvt_pk_bf16_f32 v91, v99, v100
	v_add_f32_e32 v80, 1.0, v80
	global_store_dwordx4 v[92:93], v[88:91], off nt
	v_mul_f32_e32 v84, 0xbfb8aa3b, v84
	v_mul_f32_e32 v85, 0xbfb8aa3b, v85
	v_rcp_f32_e32 v88, v80
	v_add_f32_e32 v80, 1.0, v81
	v_mul_f32_e32 v81, 0xbfb8aa3b, v82
	v_mul_f32_e32 v86, 0xbfb8aa3b, v86
	v_mul_f32_e32 v87, 0xbfb8aa3b, v87
	v_exp_f32_e32 v81, v81
	v_mul_f32_e32 v82, 0xbfb8aa3b, v83
	v_exp_f32_e32 v84, v84
	v_exp_f32_e32 v85, v85
	v_exp_f32_e32 v86, v86
	v_exp_f32_e32 v87, v87
	v_exp_f32_e32 v82, v82
	v_rcp_f32_e32 v83, v80
	v_add_f32_e32 v80, 1.0, v81
	v_add_f32_e32 v84, 1.0, v84
	v_add_f32_e32 v85, 1.0, v85
	v_add_f32_e32 v86, 1.0, v86
	v_add_f32_e32 v87, 1.0, v87
	v_rcp_f32_e32 v89, v80
	v_add_f32_e32 v80, 1.0, v82
	v_rcp_f32_e32 v84, v84
	v_rcp_f32_e32 v85, v85
	v_rcp_f32_e32 v86, v86
	v_rcp_f32_e32 v87, v87
	v_rcp_f32_e32 v90, v80
	v_mul_f32_e32 v72, 0xbfb8aa3b, v72
	v_cvt_pk_bf16_f32 v80, v84, v85
	v_cvt_pk_bf16_f32 v81, v86, v87
	v_cvt_pk_bf16_f32 v82, v88, v83
	v_cvt_pk_bf16_f32 v83, v89, v90
	v_mul_f32_e32 v76, 0xbfb8aa3b, v76
	v_exp_f32_e32 v72, v72
	v_mul_f32_e32 v73, 0xbfb8aa3b, v73
	global_store_dwordx4 v[92:93], v[80:83], off offset:256 nt
	v_exp_f32_e32 v73, v73
	v_add_f32_e32 v72, 1.0, v72
	v_exp_f32_e32 v82, v76
	v_or_b32_e32 v80, 48, v142
	v_ashrrev_i32_e32 v81, 31, v80
	v_lshlrev_b64 v[80:81], 11, v[80:81]
	v_mul_f32_e32 v76, 0xbfb8aa3b, v77
	v_exp_f32_e32 v83, v76
	v_lshl_add_u64 v[76:77], v[140:141], 0, v[80:81]
	v_add_f32_e32 v80, 1.0, v82
	v_rcp_f32_e32 v82, v72
	v_add_f32_e32 v72, 1.0, v73
	v_mul_f32_e32 v73, 0xbfb8aa3b, v74
	v_mul_f32_e32 v78, 0xbfb8aa3b, v78
	v_mul_f32_e32 v79, 0xbfb8aa3b, v79
	v_exp_f32_e32 v73, v73
	v_mul_f32_e32 v74, 0xbfb8aa3b, v75
	v_exp_f32_e32 v78, v78
	v_exp_f32_e32 v79, v79
	v_exp_f32_e32 v74, v74
	v_rcp_f32_e32 v75, v72
	v_add_f32_e32 v72, 1.0, v73
	v_add_f32_e32 v81, 1.0, v83
	v_add_f32_e32 v78, 1.0, v78
	v_add_f32_e32 v79, 1.0, v79
	v_rcp_f32_e32 v83, v72
	v_add_f32_e32 v72, 1.0, v74
	v_mul_f32_e32 v64, 0xbfb8aa3b, v64
	v_rcp_f32_e32 v80, v80
	v_rcp_f32_e32 v81, v81
	v_rcp_f32_e32 v78, v78
	v_rcp_f32_e32 v79, v79
	v_rcp_f32_e32 v84, v72
	v_exp_f32_e32 v64, v64
	v_mul_f32_e32 v65, 0xbfb8aa3b, v65
	v_exp_f32_e32 v65, v65
	v_cvt_pk_bf16_f32 v72, v80, v81
	v_cvt_pk_bf16_f32 v73, v78, v79
	v_cvt_pk_bf16_f32 v74, v82, v75
	v_cvt_pk_bf16_f32 v75, v83, v84
	v_add_f32_e32 v64, 1.0, v64
	global_store_dwordx4 v[76:77], v[72:75], off nt
	v_mul_f32_e32 v68, 0xbfb8aa3b, v68
	v_mul_f32_e32 v69, 0xbfb8aa3b, v69
	v_rcp_f32_e32 v72, v64
	v_add_f32_e32 v64, 1.0, v65
	v_mul_f32_e32 v65, 0xbfb8aa3b, v66
	v_mul_f32_e32 v70, 0xbfb8aa3b, v70
	v_mul_f32_e32 v71, 0xbfb8aa3b, v71
	v_exp_f32_e32 v65, v65
	v_mul_f32_e32 v66, 0xbfb8aa3b, v67
	v_exp_f32_e32 v68, v68
	v_exp_f32_e32 v69, v69
	v_exp_f32_e32 v70, v70
	v_exp_f32_e32 v71, v71
	v_exp_f32_e32 v66, v66
	v_rcp_f32_e32 v67, v64
	v_add_f32_e32 v64, 1.0, v65
	v_add_f32_e32 v68, 1.0, v68
	v_add_f32_e32 v69, 1.0, v69
	v_add_f32_e32 v70, 1.0, v70
	v_add_f32_e32 v71, 1.0, v71
	v_rcp_f32_e32 v73, v64
	v_add_f32_e32 v64, 1.0, v66
	v_mul_f32_e32 v56, 0xbfb8aa3b, v56
	v_rcp_f32_e32 v68, v68
	v_rcp_f32_e32 v69, v69
	v_rcp_f32_e32 v70, v70
	v_rcp_f32_e32 v71, v71
	v_rcp_f32_e32 v74, v64
	v_exp_f32_e32 v56, v56
	v_mul_f32_e32 v57, 0xbfb8aa3b, v57
	v_exp_f32_e32 v57, v57
	v_cvt_pk_bf16_f32 v64, v68, v69
	v_cvt_pk_bf16_f32 v65, v70, v71
	v_cvt_pk_bf16_f32 v66, v72, v67
	v_cvt_pk_bf16_f32 v67, v73, v74
	v_add_f32_e32 v56, 1.0, v56
	global_store_dwordx4 v[76:77], v[64:67], off offset:256 nt
	v_mul_f32_e32 v60, 0xbfb8aa3b, v60
	v_mul_f32_e32 v62, 0xbfb8aa3b, v62
	v_mul_f32_e32 v63, 0xbfb8aa3b, v63
	v_rcp_f32_e32 v66, v56
	v_add_f32_e32 v56, 1.0, v57
	v_mul_f32_e32 v57, 0xbfb8aa3b, v58
	v_exp_f32_e32 v64, v60
	v_mul_f32_e32 v60, 0xbfb8aa3b, v61
	v_exp_f32_e32 v62, v62
	v_exp_f32_e32 v63, v63
	v_exp_f32_e32 v57, v57
	v_mul_f32_e32 v58, 0xbfb8aa3b, v59
	v_exp_f32_e32 v65, v60
	v_exp_f32_e32 v58, v58
	v_add_f32_e32 v62, 1.0, v62
	v_add_f32_e32 v63, 1.0, v63
	v_rcp_f32_e32 v59, v56
	v_add_f32_e32 v56, 1.0, v57
	v_add_f32_e32 v64, 1.0, v64
	v_add_f32_e32 v65, 1.0, v65
	v_rcp_f32_e32 v62, v62
	v_rcp_f32_e32 v63, v63
	v_rcp_f32_e32 v67, v56
	v_add_f32_e32 v56, 1.0, v58
	v_mul_f32_e32 v48, 0xbfb8aa3b, v48
	v_rcp_f32_e32 v64, v64
	v_rcp_f32_e32 v65, v65
	v_rcp_f32_e32 v68, v56
	v_exp_f32_e32 v48, v48
	v_mul_f32_e32 v49, 0xbfb8aa3b, v49
	v_exp_f32_e32 v49, v49
	s_mov_b32 s1, 0x40000
	v_cvt_pk_bf16_f32 v57, v62, v63
	v_add_co_u32_e32 v62, vcc, s1, v124
	v_cvt_pk_bf16_f32 v56, v64, v65
	v_cvt_pk_bf16_f32 v58, v66, v59
	v_cvt_pk_bf16_f32 v59, v67, v68
	v_addc_co_u32_e32 v63, vcc, 0, v125, vcc
	v_add_f32_e32 v48, 1.0, v48
	global_store_dwordx4 v[62:63], v[56:59], off nt
	v_mul_f32_e32 v52, 0xbfb8aa3b, v52
	v_mul_f32_e32 v53, 0xbfb8aa3b, v53
	v_rcp_f32_e32 v56, v48
	v_add_f32_e32 v48, 1.0, v49
	v_mul_f32_e32 v49, 0xbfb8aa3b, v50
	v_mul_f32_e32 v54, 0xbfb8aa3b, v54
	v_mul_f32_e32 v55, 0xbfb8aa3b, v55
	v_exp_f32_e32 v49, v49
	v_mul_f32_e32 v50, 0xbfb8aa3b, v51
	v_exp_f32_e32 v52, v52
	v_exp_f32_e32 v53, v53
	v_exp_f32_e32 v54, v54
	v_exp_f32_e32 v55, v55
	v_exp_f32_e32 v50, v50
	v_rcp_f32_e32 v51, v48
	v_add_f32_e32 v48, 1.0, v49
	v_add_f32_e32 v52, 1.0, v52
	v_add_f32_e32 v53, 1.0, v53
	v_add_f32_e32 v54, 1.0, v54
	v_add_f32_e32 v55, 1.0, v55
	v_rcp_f32_e32 v57, v48
	v_add_f32_e32 v48, 1.0, v50
	v_mul_f32_e32 v40, 0xbfb8aa3b, v40
	v_rcp_f32_e32 v52, v52
	v_rcp_f32_e32 v53, v53
	v_rcp_f32_e32 v54, v54
	v_rcp_f32_e32 v55, v55
	v_rcp_f32_e32 v58, v48
	v_exp_f32_e32 v40, v40
	v_mul_f32_e32 v41, 0xbfb8aa3b, v41
	v_exp_f32_e32 v41, v41
	s_mov_b64 s[14:15], 0x40000
	v_lshl_add_u64 v[60:61], v[124:125], 0, s[14:15]
	v_cvt_pk_bf16_f32 v48, v52, v53
	v_cvt_pk_bf16_f32 v49, v54, v55
	v_cvt_pk_bf16_f32 v50, v56, v51
	v_cvt_pk_bf16_f32 v51, v57, v58
	v_add_f32_e32 v40, 1.0, v40
	global_store_dwordx4 v[60:61], v[48:51], off offset:256 nt
	v_mul_f32_e32 v44, 0xbfb8aa3b, v44
	v_mul_f32_e32 v46, 0xbfb8aa3b, v46
	v_mul_f32_e32 v47, 0xbfb8aa3b, v47
	v_rcp_f32_e32 v50, v40
	v_add_f32_e32 v40, 1.0, v41
	v_mul_f32_e32 v41, 0xbfb8aa3b, v42
	v_exp_f32_e32 v48, v44
	v_mul_f32_e32 v44, 0xbfb8aa3b, v45
	v_exp_f32_e32 v46, v46
	v_exp_f32_e32 v47, v47
	v_exp_f32_e32 v41, v41
	v_mul_f32_e32 v42, 0xbfb8aa3b, v43
	v_exp_f32_e32 v49, v44
	v_exp_f32_e32 v42, v42
	v_add_f32_e32 v46, 1.0, v46
	v_add_f32_e32 v47, 1.0, v47
	v_rcp_f32_e32 v43, v40
	v_add_f32_e32 v40, 1.0, v41
	v_add_f32_e32 v48, 1.0, v48
	v_add_f32_e32 v49, 1.0, v49
	v_rcp_f32_e32 v46, v46
	v_rcp_f32_e32 v47, v47
	v_rcp_f32_e32 v51, v40
	v_add_f32_e32 v40, 1.0, v42
	v_mul_f32_e32 v32, 0xbfb8aa3b, v32
	v_rcp_f32_e32 v48, v48
	v_rcp_f32_e32 v49, v49
	v_rcp_f32_e32 v52, v40
	v_exp_f32_e32 v32, v32
	v_mul_f32_e32 v33, 0xbfb8aa3b, v33
	v_exp_f32_e32 v33, v33
	s_mov_b32 s1, 0x48000
	v_cvt_pk_bf16_f32 v41, v46, v47
	v_add_co_u32_e32 v46, vcc, s1, v124
	v_cvt_pk_bf16_f32 v40, v48, v49
	v_cvt_pk_bf16_f32 v42, v50, v43
	v_cvt_pk_bf16_f32 v43, v51, v52
	v_addc_co_u32_e32 v47, vcc, 0, v125, vcc
	v_add_f32_e32 v32, 1.0, v32
	global_store_dwordx4 v[46:47], v[40:43], off nt
	v_mul_f32_e32 v36, 0xbfb8aa3b, v36
	v_mul_f32_e32 v37, 0xbfb8aa3b, v37
	v_rcp_f32_e32 v40, v32
	v_add_f32_e32 v32, 1.0, v33
	v_mul_f32_e32 v33, 0xbfb8aa3b, v34
	v_mul_f32_e32 v38, 0xbfb8aa3b, v38
	v_mul_f32_e32 v39, 0xbfb8aa3b, v39
	v_exp_f32_e32 v33, v33
	v_mul_f32_e32 v34, 0xbfb8aa3b, v35
	v_exp_f32_e32 v36, v36
	v_exp_f32_e32 v37, v37
	v_exp_f32_e32 v38, v38
	v_exp_f32_e32 v39, v39
	v_exp_f32_e32 v34, v34
	v_rcp_f32_e32 v35, v32
	v_add_f32_e32 v32, 1.0, v33
	v_add_f32_e32 v36, 1.0, v36
	v_add_f32_e32 v37, 1.0, v37
	v_add_f32_e32 v38, 1.0, v38
	v_add_f32_e32 v39, 1.0, v39
	v_rcp_f32_e32 v41, v32
	v_add_f32_e32 v32, 1.0, v34
	v_mul_f32_e32 v24, 0xbfb8aa3b, v24
	v_rcp_f32_e32 v36, v36
	v_rcp_f32_e32 v37, v37
	v_rcp_f32_e32 v38, v38
	v_rcp_f32_e32 v39, v39
	v_rcp_f32_e32 v42, v32
	v_exp_f32_e32 v24, v24
	v_mul_f32_e32 v25, 0xbfb8aa3b, v25
	v_exp_f32_e32 v25, v25
	s_mov_b64 s[14:15], 0x48000
	v_lshl_add_u64 v[44:45], v[124:125], 0, s[14:15]
	v_cvt_pk_bf16_f32 v32, v36, v37
	v_cvt_pk_bf16_f32 v33, v38, v39
	v_cvt_pk_bf16_f32 v34, v40, v35
	v_cvt_pk_bf16_f32 v35, v41, v42
	v_add_f32_e32 v24, 1.0, v24
	global_store_dwordx4 v[44:45], v[32:35], off offset:256 nt
	v_mul_f32_e32 v28, 0xbfb8aa3b, v28
	v_mul_f32_e32 v30, 0xbfb8aa3b, v30
	v_mul_f32_e32 v31, 0xbfb8aa3b, v31
	v_rcp_f32_e32 v34, v24
	v_add_f32_e32 v24, 1.0, v25
	v_mul_f32_e32 v25, 0xbfb8aa3b, v26
	v_exp_f32_e32 v32, v28
	v_mul_f32_e32 v28, 0xbfb8aa3b, v29
	v_exp_f32_e32 v30, v30
	v_exp_f32_e32 v31, v31
	v_exp_f32_e32 v25, v25
	v_mul_f32_e32 v26, 0xbfb8aa3b, v27
	v_exp_f32_e32 v33, v28
	v_exp_f32_e32 v26, v26
	v_add_f32_e32 v30, 1.0, v30
	v_add_f32_e32 v31, 1.0, v31
	v_rcp_f32_e32 v27, v24
	v_add_f32_e32 v24, 1.0, v25
	v_add_f32_e32 v32, 1.0, v32
	v_add_f32_e32 v33, 1.0, v33
	v_rcp_f32_e32 v30, v30
	v_rcp_f32_e32 v31, v31
	v_rcp_f32_e32 v35, v24
	v_add_f32_e32 v24, 1.0, v26
	v_mul_f32_e32 v16, 0xbfb8aa3b, v16
	v_rcp_f32_e32 v32, v32
	v_rcp_f32_e32 v33, v33
	v_rcp_f32_e32 v36, v24
	v_exp_f32_e32 v16, v16
	v_mul_f32_e32 v17, 0xbfb8aa3b, v17
	v_exp_f32_e32 v17, v17
	s_mov_b32 s1, 0x50000
	v_cvt_pk_bf16_f32 v25, v30, v31
	v_add_co_u32_e32 v30, vcc, s1, v124
	v_cvt_pk_bf16_f32 v24, v32, v33
	v_cvt_pk_bf16_f32 v26, v34, v27
	v_cvt_pk_bf16_f32 v27, v35, v36
	v_addc_co_u32_e32 v31, vcc, 0, v125, vcc
	v_add_f32_e32 v16, 1.0, v16
	global_store_dwordx4 v[30:31], v[24:27], off nt
	v_mul_f32_e32 v20, 0xbfb8aa3b, v20
	v_mul_f32_e32 v21, 0xbfb8aa3b, v21
	v_rcp_f32_e32 v24, v16
	v_add_f32_e32 v16, 1.0, v17
	v_mul_f32_e32 v17, 0xbfb8aa3b, v18
	v_mul_f32_e32 v22, 0xbfb8aa3b, v22
	v_mul_f32_e32 v23, 0xbfb8aa3b, v23
	v_exp_f32_e32 v17, v17
	v_mul_f32_e32 v18, 0xbfb8aa3b, v19
	v_exp_f32_e32 v20, v20
	v_exp_f32_e32 v21, v21
	v_exp_f32_e32 v22, v22
	v_exp_f32_e32 v23, v23
	v_exp_f32_e32 v18, v18
	v_rcp_f32_e32 v19, v16
	v_add_f32_e32 v16, 1.0, v17
	v_add_f32_e32 v20, 1.0, v20
	v_add_f32_e32 v21, 1.0, v21
	v_add_f32_e32 v22, 1.0, v22
	v_add_f32_e32 v23, 1.0, v23
	v_rcp_f32_e32 v25, v16
	v_add_f32_e32 v16, 1.0, v18
	v_mul_f32_e32 v8, 0xbfb8aa3b, v8
	v_rcp_f32_e32 v20, v20
	v_rcp_f32_e32 v21, v21
	v_rcp_f32_e32 v22, v22
	v_rcp_f32_e32 v23, v23
	v_rcp_f32_e32 v26, v16
	v_exp_f32_e32 v8, v8
	v_mul_f32_e32 v9, 0xbfb8aa3b, v9
	v_exp_f32_e32 v9, v9
	s_mov_b64 s[14:15], 0x50000
	v_lshl_add_u64 v[28:29], v[124:125], 0, s[14:15]
	v_cvt_pk_bf16_f32 v16, v20, v21
	v_cvt_pk_bf16_f32 v17, v22, v23
	v_cvt_pk_bf16_f32 v18, v24, v19
	v_cvt_pk_bf16_f32 v19, v25, v26
	v_add_f32_e32 v8, 1.0, v8
	global_store_dwordx4 v[28:29], v[16:19], off offset:256 nt
	v_mul_f32_e32 v12, 0xbfb8aa3b, v12
	v_mul_f32_e32 v14, 0xbfb8aa3b, v14
	v_mul_f32_e32 v15, 0xbfb8aa3b, v15
	v_rcp_f32_e32 v18, v8
	v_add_f32_e32 v8, 1.0, v9
	v_mul_f32_e32 v9, 0xbfb8aa3b, v10
	v_exp_f32_e32 v16, v12
	v_mul_f32_e32 v12, 0xbfb8aa3b, v13
	v_exp_f32_e32 v14, v14
	v_exp_f32_e32 v15, v15
	v_exp_f32_e32 v9, v9
	v_mul_f32_e32 v10, 0xbfb8aa3b, v11
	v_exp_f32_e32 v17, v12
	v_exp_f32_e32 v10, v10
	v_add_f32_e32 v14, 1.0, v14
	v_add_f32_e32 v15, 1.0, v15
	v_rcp_f32_e32 v11, v8
	v_add_f32_e32 v8, 1.0, v9
	v_add_f32_e32 v16, 1.0, v16
	v_add_f32_e32 v17, 1.0, v17
	v_rcp_f32_e32 v14, v14
	v_rcp_f32_e32 v15, v15
	v_rcp_f32_e32 v19, v8
	v_add_f32_e32 v8, 1.0, v10
	v_mul_f32_e32 v0, 0xbfb8aa3b, v0
	v_rcp_f32_e32 v16, v16
	v_rcp_f32_e32 v17, v17
	v_rcp_f32_e32 v20, v8
	v_exp_f32_e32 v0, v0
	v_mul_f32_e32 v1, 0xbfb8aa3b, v1
	v_exp_f32_e32 v1, v1
	s_mov_b32 s1, 0x58000
	v_cvt_pk_bf16_f32 v9, v14, v15
	v_add_co_u32_e32 v14, vcc, s1, v124
	v_cvt_pk_bf16_f32 v8, v16, v17
	v_cvt_pk_bf16_f32 v10, v18, v11
	v_cvt_pk_bf16_f32 v11, v19, v20
	v_addc_co_u32_e32 v15, vcc, 0, v125, vcc
	v_add_f32_e32 v0, 1.0, v0
	global_store_dwordx4 v[14:15], v[8:11], off nt
	v_mul_f32_e32 v4, 0xbfb8aa3b, v4
	v_mul_f32_e32 v5, 0xbfb8aa3b, v5
	v_rcp_f32_e32 v8, v0
	v_add_f32_e32 v0, 1.0, v1
	v_mul_f32_e32 v1, 0xbfb8aa3b, v2
	v_mul_f32_e32 v6, 0xbfb8aa3b, v6
	v_mul_f32_e32 v7, 0xbfb8aa3b, v7
	v_exp_f32_e32 v1, v1
	v_mul_f32_e32 v2, 0xbfb8aa3b, v3
	v_exp_f32_e32 v4, v4
	v_exp_f32_e32 v5, v5
	v_exp_f32_e32 v6, v6
	v_exp_f32_e32 v7, v7
	v_exp_f32_e32 v2, v2
	v_rcp_f32_e32 v3, v0
	v_add_f32_e32 v0, 1.0, v1
	v_add_f32_e32 v4, 1.0, v4
	v_add_f32_e32 v5, 1.0, v5
	v_add_f32_e32 v6, 1.0, v6
	v_add_f32_e32 v7, 1.0, v7
	v_rcp_f32_e32 v9, v0
	v_add_f32_e32 v0, 1.0, v2
	v_rcp_f32_e32 v4, v4
	v_rcp_f32_e32 v5, v5
	v_rcp_f32_e32 v6, v6
	v_rcp_f32_e32 v7, v7
	v_rcp_f32_e32 v10, v0
	s_mov_b64 s[14:15], 0x58000
	v_lshl_add_u64 v[12:13], v[124:125], 0, s[14:15]
	v_cvt_pk_bf16_f32 v0, v4, v5
	v_cvt_pk_bf16_f32 v1, v6, v7
	v_cvt_pk_bf16_f32 v2, v8, v3
	v_cvt_pk_bf16_f32 v3, v9, v10
	s_andn2_b64 vcc, exec, s[6:7]
	s_mov_b64 s[6:7], -1
	global_store_dwordx4 v[12:13], v[0:3], off offset:256 nt
	s_cbranch_vccnz .LBB0_268
	s_and_b64 vcc, exec, s[4:5]
	s_cbranch_vccnz .LBB0_267
	s_barrier
	s_branch .LBB0_267

.LBB0_293:
	s_add_i32 s1, s36, 2
	s_ashr_i32 s14, s1, 2
	s_ashr_i32 s15, s14, 31
	s_lshl_b64 s[16:17], s[14:15], 27
	s_add_u32 s9, s27, s16
	s_addc_u32 s15, s28, s17
	s_cmp_lt_i32 s14, 2
	v_mul_f32_e32 v120, 0xbfb8aa3b, v120
	s_cselect_b32 s15, s15, s30
	s_cselect_b32 s9, s9, s29
	s_lshl_b32 s1, s1, 9
	v_exp_f32_e32 v120, v120
	v_mul_f32_e32 v121, 0xbfb8aa3b, v121
	s_and_b32 s1, s1, 0x600
	v_exp_f32_e32 v121, v121
	v_lshl_add_u32 v142, s35, 8, v144
	s_add_u32 s14, s9, s1
	s_addc_u32 s15, s15, 0
	v_ashrrev_i32_e32 v143, 31, v142
	v_mul_f32_e32 v124, 0xbfb8aa3b, v124
	v_lshl_add_u64 v[140:141], v[134:135], 1, s[14:15]
	v_lshlrev_b64 v[148:149], 11, v[142:143]
	v_exp_f32_e32 v143, v124
	v_mul_f32_e32 v124, 0xbfb8aa3b, v125
	v_add_f32_e32 v120, 1.0, v120
	v_exp_f32_e32 v147, v124
	v_lshl_add_u64 v[124:125], v[140:141], 0, v[148:149]
	v_rcp_f32_e32 v148, v120
	v_add_f32_e32 v120, 1.0, v121
	v_mul_f32_e32 v121, 0xbfb8aa3b, v122
	v_mul_f32_e32 v126, 0xbfb8aa3b, v126
	v_mul_f32_e32 v127, 0xbfb8aa3b, v127
	v_exp_f32_e32 v121, v121
	v_mul_f32_e32 v122, 0xbfb8aa3b, v123
	v_exp_f32_e32 v126, v126
	v_exp_f32_e32 v127, v127
	v_exp_f32_e32 v122, v122
	v_rcp_f32_e32 v123, v120
	v_add_f32_e32 v120, 1.0, v121
	v_add_f32_e32 v143, 1.0, v143
	v_add_f32_e32 v147, 1.0, v147
	v_add_f32_e32 v126, 1.0, v126
	v_add_f32_e32 v127, 1.0, v127
	v_rcp_f32_e32 v149, v120
	v_add_f32_e32 v120, 1.0, v122
	v_mul_f32_e32 v112, 0xbfb8aa3b, v112
	v_rcp_f32_e32 v143, v143
	v_rcp_f32_e32 v147, v147
	v_rcp_f32_e32 v126, v126
	v_rcp_f32_e32 v127, v127
	v_rcp_f32_e32 v150, v120
	v_exp_f32_e32 v112, v112
	v_mul_f32_e32 v113, 0xbfb8aa3b, v113
	v_exp_f32_e32 v113, v113
	v_cvt_pk_bf16_f32 v120, v143, v147
	v_cvt_pk_bf16_f32 v121, v126, v127
	v_cvt_pk_bf16_f32 v122, v148, v123
	v_cvt_pk_bf16_f32 v123, v149, v150
	v_add_f32_e32 v112, 1.0, v112
	global_store_dwordx4 v[124:125], v[120:123], off nt
	v_mul_f32_e32 v116, 0xbfb8aa3b, v116
	v_mul_f32_e32 v117, 0xbfb8aa3b, v117
	v_rcp_f32_e32 v120, v112
	v_add_f32_e32 v112, 1.0, v113
	v_mul_f32_e32 v113, 0xbfb8aa3b, v114
	v_mul_f32_e32 v118, 0xbfb8aa3b, v118
	v_mul_f32_e32 v119, 0xbfb8aa3b, v119
	v_exp_f32_e32 v113, v113
	v_mul_f32_e32 v114, 0xbfb8aa3b, v115
	v_exp_f32_e32 v116, v116
	v_exp_f32_e32 v117, v117
	v_exp_f32_e32 v118, v118
	v_exp_f32_e32 v119, v119
	v_exp_f32_e32 v114, v114
	v_rcp_f32_e32 v115, v112
	v_add_f32_e32 v112, 1.0, v113
	v_add_f32_e32 v116, 1.0, v116
	v_add_f32_e32 v117, 1.0, v117
	v_add_f32_e32 v118, 1.0, v118
	v_add_f32_e32 v119, 1.0, v119
	v_rcp_f32_e32 v121, v112
	v_add_f32_e32 v112, 1.0, v114
	v_rcp_f32_e32 v116, v116
	v_rcp_f32_e32 v117, v117
	v_rcp_f32_e32 v118, v118
	v_rcp_f32_e32 v119, v119
	v_rcp_f32_e32 v122, v112
	v_mul_f32_e32 v104, 0xbfb8aa3b, v104
	v_cvt_pk_bf16_f32 v112, v116, v117
	v_cvt_pk_bf16_f32 v113, v118, v119
	v_cvt_pk_bf16_f32 v114, v120, v115
	v_cvt_pk_bf16_f32 v115, v121, v122
	v_mul_f32_e32 v108, 0xbfb8aa3b, v108
	v_exp_f32_e32 v104, v104
	v_mul_f32_e32 v105, 0xbfb8aa3b, v105
	global_store_dwordx4 v[124:125], v[112:115], off offset:256 nt
	v_exp_f32_e32 v105, v105
	v_add_f32_e32 v104, 1.0, v104
	v_exp_f32_e32 v114, v108
	v_or_b32_e32 v112, 16, v142
	v_ashrrev_i32_e32 v113, 31, v112
	v_lshlrev_b64 v[112:113], 11, v[112:113]
	v_mul_f32_e32 v108, 0xbfb8aa3b, v109
	v_exp_f32_e32 v115, v108
	v_lshl_add_u64 v[108:109], v[140:141], 0, v[112:113]
	v_add_f32_e32 v112, 1.0, v114
	v_rcp_f32_e32 v114, v104
	v_add_f32_e32 v104, 1.0, v105
	v_mul_f32_e32 v105, 0xbfb8aa3b, v106
	v_mul_f32_e32 v110, 0xbfb8aa3b, v110
	v_mul_f32_e32 v111, 0xbfb8aa3b, v111
	v_exp_f32_e32 v105, v105
	v_mul_f32_e32 v106, 0xbfb8aa3b, v107
	v_exp_f32_e32 v110, v110
	v_exp_f32_e32 v111, v111
	v_exp_f32_e32 v106, v106
	v_rcp_f32_e32 v107, v104
	v_add_f32_e32 v104, 1.0, v105
	v_add_f32_e32 v113, 1.0, v115
	v_add_f32_e32 v110, 1.0, v110
	v_add_f32_e32 v111, 1.0, v111
	v_rcp_f32_e32 v115, v104
	v_add_f32_e32 v104, 1.0, v106
	v_mul_f32_e32 v96, 0xbfb8aa3b, v96
	v_rcp_f32_e32 v112, v112
	v_rcp_f32_e32 v113, v113
	v_rcp_f32_e32 v110, v110
	v_rcp_f32_e32 v111, v111
	v_rcp_f32_e32 v116, v104
	v_exp_f32_e32 v96, v96
	v_mul_f32_e32 v97, 0xbfb8aa3b, v97
	v_exp_f32_e32 v97, v97
	v_cvt_pk_bf16_f32 v104, v112, v113
	v_cvt_pk_bf16_f32 v105, v110, v111
	v_cvt_pk_bf16_f32 v106, v114, v107
	v_cvt_pk_bf16_f32 v107, v115, v116
	v_add_f32_e32 v96, 1.0, v96
	global_store_dwordx4 v[108:109], v[104:107], off nt
	v_mul_f32_e32 v100, 0xbfb8aa3b, v100
	v_mul_f32_e32 v101, 0xbfb8aa3b, v101
	v_rcp_f32_e32 v104, v96
	v_add_f32_e32 v96, 1.0, v97
	v_mul_f32_e32 v97, 0xbfb8aa3b, v98
	v_mul_f32_e32 v102, 0xbfb8aa3b, v102
	v_mul_f32_e32 v103, 0xbfb8aa3b, v103
	v_exp_f32_e32 v97, v97
	v_mul_f32_e32 v98, 0xbfb8aa3b, v99
	v_exp_f32_e32 v100, v100
	v_exp_f32_e32 v101, v101
	v_exp_f32_e32 v102, v102
	v_exp_f32_e32 v103, v103
	v_exp_f32_e32 v98, v98
	v_rcp_f32_e32 v99, v96
	v_add_f32_e32 v96, 1.0, v97
	v_add_f32_e32 v100, 1.0, v100
	v_add_f32_e32 v101, 1.0, v101
	v_add_f32_e32 v102, 1.0, v102
	v_add_f32_e32 v103, 1.0, v103
	v_rcp_f32_e32 v105, v96
	v_add_f32_e32 v96, 1.0, v98
	v_rcp_f32_e32 v100, v100
	v_rcp_f32_e32 v101, v101
	v_rcp_f32_e32 v102, v102
	v_rcp_f32_e32 v103, v103
	v_rcp_f32_e32 v106, v96
	v_mul_f32_e32 v88, 0xbfb8aa3b, v88
	v_cvt_pk_bf16_f32 v96, v100, v101
	v_cvt_pk_bf16_f32 v97, v102, v103
	v_cvt_pk_bf16_f32 v98, v104, v99
	v_cvt_pk_bf16_f32 v99, v105, v106
	v_mul_f32_e32 v92, 0xbfb8aa3b, v92
	v_exp_f32_e32 v88, v88
	v_mul_f32_e32 v89, 0xbfb8aa3b, v89
	global_store_dwordx4 v[108:109], v[96:99], off offset:256 nt
	v_exp_f32_e32 v89, v89
	v_add_f32_e32 v88, 1.0, v88
	v_exp_f32_e32 v98, v92
	v_or_b32_e32 v96, 32, v142
	v_ashrrev_i32_e32 v97, 31, v96
	v_lshlrev_b64 v[96:97], 11, v[96:97]
	v_mul_f32_e32 v92, 0xbfb8aa3b, v93
	v_exp_f32_e32 v99, v92
	v_lshl_add_u64 v[92:93], v[140:141], 0, v[96:97]
	v_add_f32_e32 v96, 1.0, v98
	v_rcp_f32_e32 v98, v88
	v_add_f32_e32 v88, 1.0, v89
	v_mul_f32_e32 v89, 0xbfb8aa3b, v90
	v_mul_f32_e32 v94, 0xbfb8aa3b, v94
	v_mul_f32_e32 v95, 0xbfb8aa3b, v95
	v_exp_f32_e32 v89, v89
	v_mul_f32_e32 v90, 0xbfb8aa3b, v91
	v_exp_f32_e32 v94, v94
	v_exp_f32_e32 v95, v95
	v_exp_f32_e32 v90, v90
	v_rcp_f32_e32 v91, v88
	v_add_f32_e32 v88, 1.0, v89
	v_add_f32_e32 v97, 1.0, v99
	v_add_f32_e32 v94, 1.0, v94
	v_add_f32_e32 v95, 1.0, v95
	v_rcp_f32_e32 v99, v88
	v_add_f32_e32 v88, 1.0, v90
	v_mul_f32_e32 v80, 0xbfb8aa3b, v80
	v_rcp_f32_e32 v96, v96
	v_rcp_f32_e32 v97, v97
	v_rcp_f32_e32 v94, v94
	v_rcp_f32_e32 v95, v95
	v_rcp_f32_e32 v100, v88
	v_exp_f32_e32 v80, v80
	v_mul_f32_e32 v81, 0xbfb8aa3b, v81
	v_exp_f32_e32 v81, v81
	v_cvt_pk_bf16_f32 v88, v96, v97
	v_cvt_pk_bf16_f32 v89, v94, v95
	v_cvt_pk_bf16_f32 v90, v98, v91
	v_cvt_pk_bf16_f32 v91, v99, v100
	v_add_f32_e32 v80, 1.0, v80
	global_store_dwordx4 v[92:93], v[88:91], off nt
	v_mul_f32_e32 v84, 0xbfb8aa3b, v84
	v_mul_f32_e32 v85, 0xbfb8aa3b, v85
	v_rcp_f32_e32 v88, v80
	v_add_f32_e32 v80, 1.0, v81
	v_mul_f32_e32 v81, 0xbfb8aa3b, v82
	v_mul_f32_e32 v86, 0xbfb8aa3b, v86
	v_mul_f32_e32 v87, 0xbfb8aa3b, v87
	v_exp_f32_e32 v81, v81
	v_mul_f32_e32 v82, 0xbfb8aa3b, v83
	v_exp_f32_e32 v84, v84
	v_exp_f32_e32 v85, v85
	v_exp_f32_e32 v86, v86
	v_exp_f32_e32 v87, v87
	v_exp_f32_e32 v82, v82
	v_rcp_f32_e32 v83, v80
	v_add_f32_e32 v80, 1.0, v81
	v_add_f32_e32 v84, 1.0, v84
	v_add_f32_e32 v85, 1.0, v85
	v_add_f32_e32 v86, 1.0, v86
	v_add_f32_e32 v87, 1.0, v87
	v_rcp_f32_e32 v89, v80
	v_add_f32_e32 v80, 1.0, v82
	v_rcp_f32_e32 v84, v84
	v_rcp_f32_e32 v85, v85
	v_rcp_f32_e32 v86, v86
	v_rcp_f32_e32 v87, v87
	v_rcp_f32_e32 v90, v80
	v_mul_f32_e32 v72, 0xbfb8aa3b, v72
	v_cvt_pk_bf16_f32 v80, v84, v85
	v_cvt_pk_bf16_f32 v81, v86, v87
	v_cvt_pk_bf16_f32 v82, v88, v83
	v_cvt_pk_bf16_f32 v83, v89, v90
	v_mul_f32_e32 v76, 0xbfb8aa3b, v76
	v_exp_f32_e32 v72, v72
	v_mul_f32_e32 v73, 0xbfb8aa3b, v73
	global_store_dwordx4 v[92:93], v[80:83], off offset:256 nt
	v_exp_f32_e32 v73, v73
	v_add_f32_e32 v72, 1.0, v72
	v_exp_f32_e32 v82, v76
	v_or_b32_e32 v80, 48, v142
	v_ashrrev_i32_e32 v81, 31, v80
	v_lshlrev_b64 v[80:81], 11, v[80:81]
	v_mul_f32_e32 v76, 0xbfb8aa3b, v77
	v_exp_f32_e32 v83, v76
	v_lshl_add_u64 v[76:77], v[140:141], 0, v[80:81]
	v_add_f32_e32 v80, 1.0, v82
	v_rcp_f32_e32 v82, v72
	v_add_f32_e32 v72, 1.0, v73
	v_mul_f32_e32 v73, 0xbfb8aa3b, v74
	v_mul_f32_e32 v78, 0xbfb8aa3b, v78
	v_mul_f32_e32 v79, 0xbfb8aa3b, v79
	v_exp_f32_e32 v73, v73
	v_mul_f32_e32 v74, 0xbfb8aa3b, v75
	v_exp_f32_e32 v78, v78
	v_exp_f32_e32 v79, v79
	v_exp_f32_e32 v74, v74
	v_rcp_f32_e32 v75, v72
	v_add_f32_e32 v72, 1.0, v73
	v_add_f32_e32 v81, 1.0, v83
	v_add_f32_e32 v78, 1.0, v78
	v_add_f32_e32 v79, 1.0, v79
	v_rcp_f32_e32 v83, v72
	v_add_f32_e32 v72, 1.0, v74
	v_mul_f32_e32 v64, 0xbfb8aa3b, v64
	v_rcp_f32_e32 v80, v80
	v_rcp_f32_e32 v81, v81
	v_rcp_f32_e32 v78, v78
	v_rcp_f32_e32 v79, v79
	v_rcp_f32_e32 v84, v72
	v_exp_f32_e32 v64, v64
	v_mul_f32_e32 v65, 0xbfb8aa3b, v65
	v_exp_f32_e32 v65, v65
	v_cvt_pk_bf16_f32 v72, v80, v81
	v_cvt_pk_bf16_f32 v73, v78, v79
	v_cvt_pk_bf16_f32 v74, v82, v75
	v_cvt_pk_bf16_f32 v75, v83, v84
	v_add_f32_e32 v64, 1.0, v64
	global_store_dwordx4 v[76:77], v[72:75], off nt
	v_mul_f32_e32 v68, 0xbfb8aa3b, v68
	v_mul_f32_e32 v69, 0xbfb8aa3b, v69
	v_rcp_f32_e32 v72, v64
	v_add_f32_e32 v64, 1.0, v65
	v_mul_f32_e32 v65, 0xbfb8aa3b, v66
	v_mul_f32_e32 v70, 0xbfb8aa3b, v70
	v_mul_f32_e32 v71, 0xbfb8aa3b, v71
	v_exp_f32_e32 v65, v65
	v_mul_f32_e32 v66, 0xbfb8aa3b, v67
	v_exp_f32_e32 v68, v68
	v_exp_f32_e32 v69, v69
	v_exp_f32_e32 v70, v70
	v_exp_f32_e32 v71, v71
	v_exp_f32_e32 v66, v66
	v_rcp_f32_e32 v67, v64
	v_add_f32_e32 v64, 1.0, v65
	v_add_f32_e32 v68, 1.0, v68
	v_add_f32_e32 v69, 1.0, v69
	v_add_f32_e32 v70, 1.0, v70
	v_add_f32_e32 v71, 1.0, v71
	v_rcp_f32_e32 v73, v64
	v_add_f32_e32 v64, 1.0, v66
	v_mul_f32_e32 v56, 0xbfb8aa3b, v56
	v_rcp_f32_e32 v68, v68
	v_rcp_f32_e32 v69, v69
	v_rcp_f32_e32 v70, v70
	v_rcp_f32_e32 v71, v71
	v_rcp_f32_e32 v74, v64
	v_exp_f32_e32 v56, v56
	v_mul_f32_e32 v57, 0xbfb8aa3b, v57
	v_exp_f32_e32 v57, v57
	v_cvt_pk_bf16_f32 v64, v68, v69
	v_cvt_pk_bf16_f32 v65, v70, v71
	v_cvt_pk_bf16_f32 v66, v72, v67
	v_cvt_pk_bf16_f32 v67, v73, v74
	v_add_f32_e32 v56, 1.0, v56
	global_store_dwordx4 v[76:77], v[64:67], off offset:256 nt
	v_mul_f32_e32 v60, 0xbfb8aa3b, v60
	v_mul_f32_e32 v62, 0xbfb8aa3b, v62
	v_mul_f32_e32 v63, 0xbfb8aa3b, v63
	v_rcp_f32_e32 v66, v56
	v_add_f32_e32 v56, 1.0, v57
	v_mul_f32_e32 v57, 0xbfb8aa3b, v58
	v_exp_f32_e32 v64, v60
	v_mul_f32_e32 v60, 0xbfb8aa3b, v61
	v_exp_f32_e32 v62, v62
	v_exp_f32_e32 v63, v63
	v_exp_f32_e32 v57, v57
	v_mul_f32_e32 v58, 0xbfb8aa3b, v59
	v_exp_f32_e32 v65, v60
	v_exp_f32_e32 v58, v58
	v_add_f32_e32 v62, 1.0, v62
	v_add_f32_e32 v63, 1.0, v63
	v_rcp_f32_e32 v59, v56
	v_add_f32_e32 v56, 1.0, v57
	v_add_f32_e32 v64, 1.0, v64
	v_add_f32_e32 v65, 1.0, v65
	v_rcp_f32_e32 v62, v62
	v_rcp_f32_e32 v63, v63
	v_rcp_f32_e32 v67, v56
	v_add_f32_e32 v56, 1.0, v58
	v_mul_f32_e32 v48, 0xbfb8aa3b, v48
	v_rcp_f32_e32 v64, v64
	v_rcp_f32_e32 v65, v65
	v_rcp_f32_e32 v68, v56
	v_exp_f32_e32 v48, v48
	v_mul_f32_e32 v49, 0xbfb8aa3b, v49
	v_exp_f32_e32 v49, v49
	s_mov_b32 s1, 0x40000
	v_cvt_pk_bf16_f32 v57, v62, v63
	v_add_co_u32_e32 v62, vcc, s1, v124
	v_cvt_pk_bf16_f32 v56, v64, v65
	v_cvt_pk_bf16_f32 v58, v66, v59
	v_cvt_pk_bf16_f32 v59, v67, v68
	v_addc_co_u32_e32 v63, vcc, 0, v125, vcc
	v_add_f32_e32 v48, 1.0, v48
	global_store_dwordx4 v[62:63], v[56:59], off nt
	v_mul_f32_e32 v52, 0xbfb8aa3b, v52
	v_mul_f32_e32 v53, 0xbfb8aa3b, v53
	v_rcp_f32_e32 v56, v48
	v_add_f32_e32 v48, 1.0, v49
	v_mul_f32_e32 v49, 0xbfb8aa3b, v50
	v_mul_f32_e32 v54, 0xbfb8aa3b, v54
	v_mul_f32_e32 v55, 0xbfb8aa3b, v55
	v_exp_f32_e32 v49, v49
	v_mul_f32_e32 v50, 0xbfb8aa3b, v51
	v_exp_f32_e32 v52, v52
	v_exp_f32_e32 v53, v53
	v_exp_f32_e32 v54, v54
	v_exp_f32_e32 v55, v55
	v_exp_f32_e32 v50, v50
	v_rcp_f32_e32 v51, v48
	v_add_f32_e32 v48, 1.0, v49
	v_add_f32_e32 v52, 1.0, v52
	v_add_f32_e32 v53, 1.0, v53
	v_add_f32_e32 v54, 1.0, v54
	v_add_f32_e32 v55, 1.0, v55
	v_rcp_f32_e32 v57, v48
	v_add_f32_e32 v48, 1.0, v50
	v_mul_f32_e32 v40, 0xbfb8aa3b, v40
	v_rcp_f32_e32 v52, v52
	v_rcp_f32_e32 v53, v53
	v_rcp_f32_e32 v54, v54
	v_rcp_f32_e32 v55, v55
	v_rcp_f32_e32 v58, v48
	v_exp_f32_e32 v40, v40
	v_mul_f32_e32 v41, 0xbfb8aa3b, v41
	v_exp_f32_e32 v41, v41
	s_mov_b64 s[14:15], 0x40000
	v_lshl_add_u64 v[60:61], v[124:125], 0, s[14:15]
	v_cvt_pk_bf16_f32 v48, v52, v53
	v_cvt_pk_bf16_f32 v49, v54, v55
	v_cvt_pk_bf16_f32 v50, v56, v51
	v_cvt_pk_bf16_f32 v51, v57, v58
	v_add_f32_e32 v40, 1.0, v40
	global_store_dwordx4 v[60:61], v[48:51], off offset:256 nt
	v_mul_f32_e32 v44, 0xbfb8aa3b, v44
	v_mul_f32_e32 v46, 0xbfb8aa3b, v46
	v_mul_f32_e32 v47, 0xbfb8aa3b, v47
	v_rcp_f32_e32 v50, v40
	v_add_f32_e32 v40, 1.0, v41
	v_mul_f32_e32 v41, 0xbfb8aa3b, v42
	v_exp_f32_e32 v48, v44
	v_mul_f32_e32 v44, 0xbfb8aa3b, v45
	v_exp_f32_e32 v46, v46
	v_exp_f32_e32 v47, v47
	v_exp_f32_e32 v41, v41
	v_mul_f32_e32 v42, 0xbfb8aa3b, v43
	v_exp_f32_e32 v49, v44
	v_exp_f32_e32 v42, v42
	v_add_f32_e32 v46, 1.0, v46
	v_add_f32_e32 v47, 1.0, v47
	v_rcp_f32_e32 v43, v40
	v_add_f32_e32 v40, 1.0, v41
	v_add_f32_e32 v48, 1.0, v48
	v_add_f32_e32 v49, 1.0, v49
	v_rcp_f32_e32 v46, v46
	v_rcp_f32_e32 v47, v47
	v_rcp_f32_e32 v51, v40
	v_add_f32_e32 v40, 1.0, v42
	v_mul_f32_e32 v32, 0xbfb8aa3b, v32
	v_rcp_f32_e32 v48, v48
	v_rcp_f32_e32 v49, v49
	v_rcp_f32_e32 v52, v40
	v_exp_f32_e32 v32, v32
	v_mul_f32_e32 v33, 0xbfb8aa3b, v33
	v_exp_f32_e32 v33, v33
	s_mov_b32 s1, 0x48000
	v_cvt_pk_bf16_f32 v41, v46, v47
	v_add_co_u32_e32 v46, vcc, s1, v124
	v_cvt_pk_bf16_f32 v40, v48, v49
	v_cvt_pk_bf16_f32 v42, v50, v43
	v_cvt_pk_bf16_f32 v43, v51, v52
	v_addc_co_u32_e32 v47, vcc, 0, v125, vcc
	v_add_f32_e32 v32, 1.0, v32
	global_store_dwordx4 v[46:47], v[40:43], off nt
	v_mul_f32_e32 v36, 0xbfb8aa3b, v36
	v_mul_f32_e32 v37, 0xbfb8aa3b, v37
	v_rcp_f32_e32 v40, v32
	v_add_f32_e32 v32, 1.0, v33
	v_mul_f32_e32 v33, 0xbfb8aa3b, v34
	v_mul_f32_e32 v38, 0xbfb8aa3b, v38
	v_mul_f32_e32 v39, 0xbfb8aa3b, v39
	v_exp_f32_e32 v33, v33
	v_mul_f32_e32 v34, 0xbfb8aa3b, v35
	v_exp_f32_e32 v36, v36
	v_exp_f32_e32 v37, v37
	v_exp_f32_e32 v38, v38
	v_exp_f32_e32 v39, v39
	v_exp_f32_e32 v34, v34
	v_rcp_f32_e32 v35, v32
	v_add_f32_e32 v32, 1.0, v33
	v_add_f32_e32 v36, 1.0, v36
	v_add_f32_e32 v37, 1.0, v37
	v_add_f32_e32 v38, 1.0, v38
	v_add_f32_e32 v39, 1.0, v39
	v_rcp_f32_e32 v41, v32
	v_add_f32_e32 v32, 1.0, v34
	v_mul_f32_e32 v24, 0xbfb8aa3b, v24
	v_rcp_f32_e32 v36, v36
	v_rcp_f32_e32 v37, v37
	v_rcp_f32_e32 v38, v38
	v_rcp_f32_e32 v39, v39
	v_rcp_f32_e32 v42, v32
	v_exp_f32_e32 v24, v24
	v_mul_f32_e32 v25, 0xbfb8aa3b, v25
	v_exp_f32_e32 v25, v25
	s_mov_b64 s[14:15], 0x48000
	v_lshl_add_u64 v[44:45], v[124:125], 0, s[14:15]
	v_cvt_pk_bf16_f32 v32, v36, v37
	v_cvt_pk_bf16_f32 v33, v38, v39
	v_cvt_pk_bf16_f32 v34, v40, v35
	v_cvt_pk_bf16_f32 v35, v41, v42
	v_add_f32_e32 v24, 1.0, v24
	global_store_dwordx4 v[44:45], v[32:35], off offset:256 nt
	v_mul_f32_e32 v28, 0xbfb8aa3b, v28
	v_mul_f32_e32 v30, 0xbfb8aa3b, v30
	v_mul_f32_e32 v31, 0xbfb8aa3b, v31
	v_rcp_f32_e32 v34, v24
	v_add_f32_e32 v24, 1.0, v25
	v_mul_f32_e32 v25, 0xbfb8aa3b, v26
	v_exp_f32_e32 v32, v28
	v_mul_f32_e32 v28, 0xbfb8aa3b, v29
	v_exp_f32_e32 v30, v30
	v_exp_f32_e32 v31, v31
	v_exp_f32_e32 v25, v25
	v_mul_f32_e32 v26, 0xbfb8aa3b, v27
	v_exp_f32_e32 v33, v28
	v_exp_f32_e32 v26, v26
	v_add_f32_e32 v30, 1.0, v30
	v_add_f32_e32 v31, 1.0, v31
	v_rcp_f32_e32 v27, v24
	v_add_f32_e32 v24, 1.0, v25
	v_add_f32_e32 v32, 1.0, v32
	v_add_f32_e32 v33, 1.0, v33
	v_rcp_f32_e32 v30, v30
	v_rcp_f32_e32 v31, v31
	v_rcp_f32_e32 v35, v24
	v_add_f32_e32 v24, 1.0, v26
	v_mul_f32_e32 v16, 0xbfb8aa3b, v16
	v_rcp_f32_e32 v32, v32
	v_rcp_f32_e32 v33, v33
	v_rcp_f32_e32 v36, v24
	v_exp_f32_e32 v16, v16
	v_mul_f32_e32 v17, 0xbfb8aa3b, v17
	v_exp_f32_e32 v17, v17
	s_mov_b32 s1, 0x50000
	v_cvt_pk_bf16_f32 v25, v30, v31
	v_add_co_u32_e32 v30, vcc, s1, v124
	v_cvt_pk_bf16_f32 v24, v32, v33
	v_cvt_pk_bf16_f32 v26, v34, v27
	v_cvt_pk_bf16_f32 v27, v35, v36
	v_addc_co_u32_e32 v31, vcc, 0, v125, vcc
	v_add_f32_e32 v16, 1.0, v16
	global_store_dwordx4 v[30:31], v[24:27], off nt
	v_mul_f32_e32 v20, 0xbfb8aa3b, v20
	v_mul_f32_e32 v21, 0xbfb8aa3b, v21
	v_rcp_f32_e32 v24, v16
	v_add_f32_e32 v16, 1.0, v17
	v_mul_f32_e32 v17, 0xbfb8aa3b, v18
	v_mul_f32_e32 v22, 0xbfb8aa3b, v22
	v_mul_f32_e32 v23, 0xbfb8aa3b, v23
	v_exp_f32_e32 v17, v17
	v_mul_f32_e32 v18, 0xbfb8aa3b, v19
	v_exp_f32_e32 v20, v20
	v_exp_f32_e32 v21, v21
	v_exp_f32_e32 v22, v22
	v_exp_f32_e32 v23, v23
	v_exp_f32_e32 v18, v18
	v_rcp_f32_e32 v19, v16
	v_add_f32_e32 v16, 1.0, v17
	v_add_f32_e32 v20, 1.0, v20
	v_add_f32_e32 v21, 1.0, v21
	v_add_f32_e32 v22, 1.0, v22
	v_add_f32_e32 v23, 1.0, v23
	v_rcp_f32_e32 v25, v16
	v_add_f32_e32 v16, 1.0, v18
	v_mul_f32_e32 v8, 0xbfb8aa3b, v8
	v_rcp_f32_e32 v20, v20
	v_rcp_f32_e32 v21, v21
	v_rcp_f32_e32 v22, v22
	v_rcp_f32_e32 v23, v23
	v_rcp_f32_e32 v26, v16
	v_exp_f32_e32 v8, v8
	v_mul_f32_e32 v9, 0xbfb8aa3b, v9
	v_exp_f32_e32 v9, v9
	s_mov_b64 s[14:15], 0x50000
	v_lshl_add_u64 v[28:29], v[124:125], 0, s[14:15]
	v_cvt_pk_bf16_f32 v16, v20, v21
	v_cvt_pk_bf16_f32 v17, v22, v23
	v_cvt_pk_bf16_f32 v18, v24, v19
	v_cvt_pk_bf16_f32 v19, v25, v26
	v_add_f32_e32 v8, 1.0, v8
	global_store_dwordx4 v[28:29], v[16:19], off offset:256 nt
	v_mul_f32_e32 v12, 0xbfb8aa3b, v12
	v_mul_f32_e32 v14, 0xbfb8aa3b, v14
	v_mul_f32_e32 v15, 0xbfb8aa3b, v15
	v_rcp_f32_e32 v18, v8
	v_add_f32_e32 v8, 1.0, v9
	v_mul_f32_e32 v9, 0xbfb8aa3b, v10
	v_exp_f32_e32 v16, v12
	v_mul_f32_e32 v12, 0xbfb8aa3b, v13
	v_exp_f32_e32 v14, v14
	v_exp_f32_e32 v15, v15
	v_exp_f32_e32 v9, v9
	v_mul_f32_e32 v10, 0xbfb8aa3b, v11
	v_exp_f32_e32 v17, v12
	v_exp_f32_e32 v10, v10
	v_add_f32_e32 v14, 1.0, v14
	v_add_f32_e32 v15, 1.0, v15
	v_rcp_f32_e32 v11, v8
	v_add_f32_e32 v8, 1.0, v9
	v_add_f32_e32 v16, 1.0, v16
	v_add_f32_e32 v17, 1.0, v17
	v_rcp_f32_e32 v14, v14
	v_rcp_f32_e32 v15, v15
	v_rcp_f32_e32 v19, v8
	v_add_f32_e32 v8, 1.0, v10
	v_mul_f32_e32 v0, 0xbfb8aa3b, v0
	v_rcp_f32_e32 v16, v16
	v_rcp_f32_e32 v17, v17
	v_rcp_f32_e32 v20, v8
	v_exp_f32_e32 v0, v0
	v_mul_f32_e32 v1, 0xbfb8aa3b, v1
	v_exp_f32_e32 v1, v1
	s_mov_b32 s1, 0x58000
	v_cvt_pk_bf16_f32 v9, v14, v15
	v_add_co_u32_e32 v14, vcc, s1, v124
	v_cvt_pk_bf16_f32 v8, v16, v17
	v_cvt_pk_bf16_f32 v10, v18, v11
	v_cvt_pk_bf16_f32 v11, v19, v20
	v_addc_co_u32_e32 v15, vcc, 0, v125, vcc
	v_add_f32_e32 v0, 1.0, v0
	global_store_dwordx4 v[14:15], v[8:11], off nt
	v_mul_f32_e32 v4, 0xbfb8aa3b, v4
	v_mul_f32_e32 v5, 0xbfb8aa3b, v5
	v_rcp_f32_e32 v8, v0
	v_add_f32_e32 v0, 1.0, v1
	v_mul_f32_e32 v1, 0xbfb8aa3b, v2
	v_mul_f32_e32 v6, 0xbfb8aa3b, v6
	v_mul_f32_e32 v7, 0xbfb8aa3b, v7
	v_exp_f32_e32 v1, v1
	v_mul_f32_e32 v2, 0xbfb8aa3b, v3
	v_exp_f32_e32 v4, v4
	v_exp_f32_e32 v5, v5
	v_exp_f32_e32 v6, v6
	v_exp_f32_e32 v7, v7
	v_exp_f32_e32 v2, v2
	v_rcp_f32_e32 v3, v0
	v_add_f32_e32 v0, 1.0, v1
	v_add_f32_e32 v4, 1.0, v4
	v_add_f32_e32 v5, 1.0, v5
	v_add_f32_e32 v6, 1.0, v6
	v_add_f32_e32 v7, 1.0, v7
	v_rcp_f32_e32 v9, v0
	v_add_f32_e32 v0, 1.0, v2
	v_rcp_f32_e32 v4, v4
	v_rcp_f32_e32 v5, v5
	v_rcp_f32_e32 v6, v6
	v_rcp_f32_e32 v7, v7
	v_rcp_f32_e32 v10, v0
	s_mov_b64 s[14:15], 0x58000
	v_lshl_add_u64 v[12:13], v[124:125], 0, s[14:15]
	v_cvt_pk_bf16_f32 v0, v4, v5
	v_cvt_pk_bf16_f32 v1, v6, v7
	v_cvt_pk_bf16_f32 v2, v8, v3
	v_cvt_pk_bf16_f32 v3, v9, v10
	s_andn2_b64 vcc, exec, s[6:7]
	s_mov_b64 s[6:7], -1
	global_store_dwordx4 v[12:13], v[0:3], off offset:256 nt
	s_cbranch_vccnz .LBB0_286
	s_and_b64 vcc, exec, s[4:5]
	s_cbranch_vccnz .LBB0_285
	s_barrier
	s_branch .LBB0_285

.LBB0_466:
	s_ashr_i32 s14, s35, 2
	s_ashr_i32 s15, s14, 31
	s_lshl_b64 s[16:17], s[14:15], 27
	s_add_u32 s1, s27, s16
	s_addc_u32 s9, s28, s17
	s_cmp_lt_i32 s14, 2
	v_mul_f32_e32 v120, 0xbfb8aa3b, v120
	s_cselect_b32 s9, s9, s30
	s_cselect_b32 s1, s1, s29
	s_lshl_b32 s14, s35, 9
	v_exp_f32_e32 v120, v120
	v_mul_f32_e32 v121, 0xbfb8aa3b, v121
	s_and_b32 s14, s14, 0x600
	v_exp_f32_e32 v121, v121
	v_lshl_add_u32 v142, s36, 8, v144
	s_add_u32 s14, s1, s14
	s_addc_u32 s15, s9, 0
	v_ashrrev_i32_e32 v143, 31, v142
	v_mul_f32_e32 v124, 0xbfb8aa3b, v124
	v_lshl_add_u64 v[140:141], v[134:135], 1, s[14:15]
	v_lshlrev_b64 v[148:149], 11, v[142:143]
	v_exp_f32_e32 v143, v124
	v_mul_f32_e32 v124, 0xbfb8aa3b, v125
	v_add_f32_e32 v120, 1.0, v120
	v_exp_f32_e32 v147, v124
	v_lshl_add_u64 v[124:125], v[140:141], 0, v[148:149]
	v_rcp_f32_e32 v148, v120
	v_add_f32_e32 v120, 1.0, v121
	v_mul_f32_e32 v121, 0xbfb8aa3b, v122
	v_mul_f32_e32 v126, 0xbfb8aa3b, v126
	v_mul_f32_e32 v127, 0xbfb8aa3b, v127
	v_exp_f32_e32 v121, v121
	v_mul_f32_e32 v122, 0xbfb8aa3b, v123
	v_exp_f32_e32 v126, v126
	v_exp_f32_e32 v127, v127
	v_exp_f32_e32 v122, v122
	v_rcp_f32_e32 v123, v120
	v_add_f32_e32 v120, 1.0, v121
	v_add_f32_e32 v143, 1.0, v143
	v_add_f32_e32 v147, 1.0, v147
	v_add_f32_e32 v126, 1.0, v126
	v_add_f32_e32 v127, 1.0, v127
	v_rcp_f32_e32 v149, v120
	v_add_f32_e32 v120, 1.0, v122
	v_mul_f32_e32 v112, 0xbfb8aa3b, v112
	v_rcp_f32_e32 v143, v143
	v_rcp_f32_e32 v147, v147
	v_rcp_f32_e32 v126, v126
	v_rcp_f32_e32 v127, v127
	v_rcp_f32_e32 v150, v120
	v_exp_f32_e32 v112, v112
	v_mul_f32_e32 v113, 0xbfb8aa3b, v113
	v_exp_f32_e32 v113, v113
	v_cvt_pk_bf16_f32 v120, v143, v147
	v_cvt_pk_bf16_f32 v121, v126, v127
	v_cvt_pk_bf16_f32 v122, v148, v123
	v_cvt_pk_bf16_f32 v123, v149, v150
	v_add_f32_e32 v112, 1.0, v112
	global_store_dwordx4 v[124:125], v[120:123], off nt
	v_mul_f32_e32 v116, 0xbfb8aa3b, v116
	v_mul_f32_e32 v117, 0xbfb8aa3b, v117
	v_rcp_f32_e32 v120, v112
	v_add_f32_e32 v112, 1.0, v113
	v_mul_f32_e32 v113, 0xbfb8aa3b, v114
	v_mul_f32_e32 v118, 0xbfb8aa3b, v118
	v_mul_f32_e32 v119, 0xbfb8aa3b, v119
	v_exp_f32_e32 v113, v113
	v_mul_f32_e32 v114, 0xbfb8aa3b, v115
	v_exp_f32_e32 v116, v116
	v_exp_f32_e32 v117, v117
	v_exp_f32_e32 v118, v118
	v_exp_f32_e32 v119, v119
	v_exp_f32_e32 v114, v114
	v_rcp_f32_e32 v115, v112
	v_add_f32_e32 v112, 1.0, v113
	v_add_f32_e32 v116, 1.0, v116
	v_add_f32_e32 v117, 1.0, v117
	v_add_f32_e32 v118, 1.0, v118
	v_add_f32_e32 v119, 1.0, v119
	v_rcp_f32_e32 v121, v112
	v_add_f32_e32 v112, 1.0, v114
	v_rcp_f32_e32 v116, v116
	v_rcp_f32_e32 v117, v117
	v_rcp_f32_e32 v118, v118
	v_rcp_f32_e32 v119, v119
	v_rcp_f32_e32 v122, v112
	v_mul_f32_e32 v104, 0xbfb8aa3b, v104
	v_cvt_pk_bf16_f32 v112, v116, v117
	v_cvt_pk_bf16_f32 v113, v118, v119
	v_cvt_pk_bf16_f32 v114, v120, v115
	v_cvt_pk_bf16_f32 v115, v121, v122
	v_mul_f32_e32 v108, 0xbfb8aa3b, v108
	v_exp_f32_e32 v104, v104
	v_mul_f32_e32 v105, 0xbfb8aa3b, v105
	global_store_dwordx4 v[124:125], v[112:115], off offset:256 nt
	v_exp_f32_e32 v105, v105
	v_add_f32_e32 v104, 1.0, v104
	v_exp_f32_e32 v114, v108
	v_or_b32_e32 v112, 16, v142
	v_ashrrev_i32_e32 v113, 31, v112
	v_lshlrev_b64 v[112:113], 11, v[112:113]
	v_mul_f32_e32 v108, 0xbfb8aa3b, v109
	v_exp_f32_e32 v115, v108
	v_lshl_add_u64 v[108:109], v[140:141], 0, v[112:113]
	v_add_f32_e32 v112, 1.0, v114
	v_rcp_f32_e32 v114, v104
	v_add_f32_e32 v104, 1.0, v105
	v_mul_f32_e32 v105, 0xbfb8aa3b, v106
	v_mul_f32_e32 v110, 0xbfb8aa3b, v110
	v_mul_f32_e32 v111, 0xbfb8aa3b, v111
	v_exp_f32_e32 v105, v105
	v_mul_f32_e32 v106, 0xbfb8aa3b, v107
	v_exp_f32_e32 v110, v110
	v_exp_f32_e32 v111, v111
	v_exp_f32_e32 v106, v106
	v_rcp_f32_e32 v107, v104
	v_add_f32_e32 v104, 1.0, v105
	v_add_f32_e32 v113, 1.0, v115
	v_add_f32_e32 v110, 1.0, v110
	v_add_f32_e32 v111, 1.0, v111
	v_rcp_f32_e32 v115, v104
	v_add_f32_e32 v104, 1.0, v106
	v_mul_f32_e32 v96, 0xbfb8aa3b, v96
	v_rcp_f32_e32 v112, v112
	v_rcp_f32_e32 v113, v113
	v_rcp_f32_e32 v110, v110
	v_rcp_f32_e32 v111, v111
	v_rcp_f32_e32 v116, v104
	v_exp_f32_e32 v96, v96
	v_mul_f32_e32 v97, 0xbfb8aa3b, v97
	v_exp_f32_e32 v97, v97
	v_cvt_pk_bf16_f32 v104, v112, v113
	v_cvt_pk_bf16_f32 v105, v110, v111
	v_cvt_pk_bf16_f32 v106, v114, v107
	v_cvt_pk_bf16_f32 v107, v115, v116
	v_add_f32_e32 v96, 1.0, v96
	global_store_dwordx4 v[108:109], v[104:107], off nt
	v_mul_f32_e32 v100, 0xbfb8aa3b, v100
	v_mul_f32_e32 v101, 0xbfb8aa3b, v101
	v_rcp_f32_e32 v104, v96
	v_add_f32_e32 v96, 1.0, v97
	v_mul_f32_e32 v97, 0xbfb8aa3b, v98
	v_mul_f32_e32 v102, 0xbfb8aa3b, v102
	v_mul_f32_e32 v103, 0xbfb8aa3b, v103
	v_exp_f32_e32 v97, v97
	v_mul_f32_e32 v98, 0xbfb8aa3b, v99
	v_exp_f32_e32 v100, v100
	v_exp_f32_e32 v101, v101
	v_exp_f32_e32 v102, v102
	v_exp_f32_e32 v103, v103
	v_exp_f32_e32 v98, v98
	v_rcp_f32_e32 v99, v96
	v_add_f32_e32 v96, 1.0, v97
	v_add_f32_e32 v100, 1.0, v100
	v_add_f32_e32 v101, 1.0, v101
	v_add_f32_e32 v102, 1.0, v102
	v_add_f32_e32 v103, 1.0, v103
	v_rcp_f32_e32 v105, v96
	v_add_f32_e32 v96, 1.0, v98
	v_rcp_f32_e32 v100, v100
	v_rcp_f32_e32 v101, v101
	v_rcp_f32_e32 v102, v102
	v_rcp_f32_e32 v103, v103
	v_rcp_f32_e32 v106, v96
	v_mul_f32_e32 v88, 0xbfb8aa3b, v88
	v_cvt_pk_bf16_f32 v96, v100, v101
	v_cvt_pk_bf16_f32 v97, v102, v103
	v_cvt_pk_bf16_f32 v98, v104, v99
	v_cvt_pk_bf16_f32 v99, v105, v106
	v_mul_f32_e32 v92, 0xbfb8aa3b, v92
	v_exp_f32_e32 v88, v88
	v_mul_f32_e32 v89, 0xbfb8aa3b, v89
	global_store_dwordx4 v[108:109], v[96:99], off offset:256 nt
	v_exp_f32_e32 v89, v89
	v_add_f32_e32 v88, 1.0, v88
	v_exp_f32_e32 v98, v92
	v_or_b32_e32 v96, 32, v142
	v_ashrrev_i32_e32 v97, 31, v96
	v_lshlrev_b64 v[96:97], 11, v[96:97]
	v_mul_f32_e32 v92, 0xbfb8aa3b, v93
	v_exp_f32_e32 v99, v92
	v_lshl_add_u64 v[92:93], v[140:141], 0, v[96:97]
	v_add_f32_e32 v96, 1.0, v98
	v_rcp_f32_e32 v98, v88
	v_add_f32_e32 v88, 1.0, v89
	v_mul_f32_e32 v89, 0xbfb8aa3b, v90
	v_mul_f32_e32 v94, 0xbfb8aa3b, v94
	v_mul_f32_e32 v95, 0xbfb8aa3b, v95
	v_exp_f32_e32 v89, v89
	v_mul_f32_e32 v90, 0xbfb8aa3b, v91
	v_exp_f32_e32 v94, v94
	v_exp_f32_e32 v95, v95
	v_exp_f32_e32 v90, v90
	v_rcp_f32_e32 v91, v88
	v_add_f32_e32 v88, 1.0, v89
	v_add_f32_e32 v97, 1.0, v99
	v_add_f32_e32 v94, 1.0, v94
	v_add_f32_e32 v95, 1.0, v95
	v_rcp_f32_e32 v99, v88
	v_add_f32_e32 v88, 1.0, v90
	v_mul_f32_e32 v80, 0xbfb8aa3b, v80
	v_rcp_f32_e32 v96, v96
	v_rcp_f32_e32 v97, v97
	v_rcp_f32_e32 v94, v94
	v_rcp_f32_e32 v95, v95
	v_rcp_f32_e32 v100, v88
	v_exp_f32_e32 v80, v80
	v_mul_f32_e32 v81, 0xbfb8aa3b, v81
	v_exp_f32_e32 v81, v81
	v_cvt_pk_bf16_f32 v88, v96, v97
	v_cvt_pk_bf16_f32 v89, v94, v95
	v_cvt_pk_bf16_f32 v90, v98, v91
	v_cvt_pk_bf16_f32 v91, v99, v100
	v_add_f32_e32 v80, 1.0, v80
	global_store_dwordx4 v[92:93], v[88:91], off nt
	v_mul_f32_e32 v84, 0xbfb8aa3b, v84
	v_mul_f32_e32 v85, 0xbfb8aa3b, v85
	v_rcp_f32_e32 v88, v80
	v_add_f32_e32 v80, 1.0, v81
	v_mul_f32_e32 v81, 0xbfb8aa3b, v82
	v_mul_f32_e32 v86, 0xbfb8aa3b, v86
	v_mul_f32_e32 v87, 0xbfb8aa3b, v87
	v_exp_f32_e32 v81, v81
	v_mul_f32_e32 v82, 0xbfb8aa3b, v83
	v_exp_f32_e32 v84, v84
	v_exp_f32_e32 v85, v85
	v_exp_f32_e32 v86, v86
	v_exp_f32_e32 v87, v87
	v_exp_f32_e32 v82, v82
	v_rcp_f32_e32 v83, v80
	v_add_f32_e32 v80, 1.0, v81
	v_add_f32_e32 v84, 1.0, v84
	v_add_f32_e32 v85, 1.0, v85
	v_add_f32_e32 v86, 1.0, v86
	v_add_f32_e32 v87, 1.0, v87
	v_rcp_f32_e32 v89, v80
	v_add_f32_e32 v80, 1.0, v82
	v_rcp_f32_e32 v84, v84
	v_rcp_f32_e32 v85, v85
	v_rcp_f32_e32 v86, v86
	v_rcp_f32_e32 v87, v87
	v_rcp_f32_e32 v90, v80
	v_mul_f32_e32 v72, 0xbfb8aa3b, v72
	v_cvt_pk_bf16_f32 v80, v84, v85
	v_cvt_pk_bf16_f32 v81, v86, v87
	v_cvt_pk_bf16_f32 v82, v88, v83
	v_cvt_pk_bf16_f32 v83, v89, v90
	v_mul_f32_e32 v76, 0xbfb8aa3b, v76
	v_exp_f32_e32 v72, v72
	v_mul_f32_e32 v73, 0xbfb8aa3b, v73
	global_store_dwordx4 v[92:93], v[80:83], off offset:256 nt
	v_exp_f32_e32 v73, v73
	v_add_f32_e32 v72, 1.0, v72
	v_exp_f32_e32 v82, v76
	v_or_b32_e32 v80, 48, v142
	v_ashrrev_i32_e32 v81, 31, v80
	v_lshlrev_b64 v[80:81], 11, v[80:81]
	v_mul_f32_e32 v76, 0xbfb8aa3b, v77
	v_exp_f32_e32 v83, v76
	v_lshl_add_u64 v[76:77], v[140:141], 0, v[80:81]
	v_add_f32_e32 v80, 1.0, v82
	v_rcp_f32_e32 v82, v72
	v_add_f32_e32 v72, 1.0, v73
	v_mul_f32_e32 v73, 0xbfb8aa3b, v74
	v_mul_f32_e32 v78, 0xbfb8aa3b, v78
	v_mul_f32_e32 v79, 0xbfb8aa3b, v79
	v_exp_f32_e32 v73, v73
	v_mul_f32_e32 v74, 0xbfb8aa3b, v75
	v_exp_f32_e32 v78, v78
	v_exp_f32_e32 v79, v79
	v_exp_f32_e32 v74, v74
	v_rcp_f32_e32 v75, v72
	v_add_f32_e32 v72, 1.0, v73
	v_add_f32_e32 v81, 1.0, v83
	v_add_f32_e32 v78, 1.0, v78
	v_add_f32_e32 v79, 1.0, v79
	v_rcp_f32_e32 v83, v72
	v_add_f32_e32 v72, 1.0, v74
	v_mul_f32_e32 v64, 0xbfb8aa3b, v64
	v_rcp_f32_e32 v80, v80
	v_rcp_f32_e32 v81, v81
	v_rcp_f32_e32 v78, v78
	v_rcp_f32_e32 v79, v79
	v_rcp_f32_e32 v84, v72
	v_exp_f32_e32 v64, v64
	v_mul_f32_e32 v65, 0xbfb8aa3b, v65
	v_exp_f32_e32 v65, v65
	v_cvt_pk_bf16_f32 v72, v80, v81
	v_cvt_pk_bf16_f32 v73, v78, v79
	v_cvt_pk_bf16_f32 v74, v82, v75
	v_cvt_pk_bf16_f32 v75, v83, v84
	v_add_f32_e32 v64, 1.0, v64
	global_store_dwordx4 v[76:77], v[72:75], off nt
	v_mul_f32_e32 v68, 0xbfb8aa3b, v68
	v_mul_f32_e32 v69, 0xbfb8aa3b, v69
	v_rcp_f32_e32 v72, v64
	v_add_f32_e32 v64, 1.0, v65
	v_mul_f32_e32 v65, 0xbfb8aa3b, v66
	v_mul_f32_e32 v70, 0xbfb8aa3b, v70
	v_mul_f32_e32 v71, 0xbfb8aa3b, v71
	v_exp_f32_e32 v65, v65
	v_mul_f32_e32 v66, 0xbfb8aa3b, v67
	v_exp_f32_e32 v68, v68
	v_exp_f32_e32 v69, v69
	v_exp_f32_e32 v70, v70
	v_exp_f32_e32 v71, v71
	v_exp_f32_e32 v66, v66
	v_rcp_f32_e32 v67, v64
	v_add_f32_e32 v64, 1.0, v65
	v_add_f32_e32 v68, 1.0, v68
	v_add_f32_e32 v69, 1.0, v69
	v_add_f32_e32 v70, 1.0, v70
	v_add_f32_e32 v71, 1.0, v71
	v_rcp_f32_e32 v73, v64
	v_add_f32_e32 v64, 1.0, v66
	v_mul_f32_e32 v56, 0xbfb8aa3b, v56
	v_rcp_f32_e32 v68, v68
	v_rcp_f32_e32 v69, v69
	v_rcp_f32_e32 v70, v70
	v_rcp_f32_e32 v71, v71
	v_rcp_f32_e32 v74, v64
	v_exp_f32_e32 v56, v56
	v_mul_f32_e32 v57, 0xbfb8aa3b, v57
	v_exp_f32_e32 v57, v57
	v_cvt_pk_bf16_f32 v64, v68, v69
	v_cvt_pk_bf16_f32 v65, v70, v71
	v_cvt_pk_bf16_f32 v66, v72, v67
	v_cvt_pk_bf16_f32 v67, v73, v74
	v_add_f32_e32 v56, 1.0, v56
	global_store_dwordx4 v[76:77], v[64:67], off offset:256 nt
	v_mul_f32_e32 v60, 0xbfb8aa3b, v60
	v_mul_f32_e32 v62, 0xbfb8aa3b, v62
	v_mul_f32_e32 v63, 0xbfb8aa3b, v63
	v_rcp_f32_e32 v66, v56
	v_add_f32_e32 v56, 1.0, v57
	v_mul_f32_e32 v57, 0xbfb8aa3b, v58
	v_exp_f32_e32 v64, v60
	v_mul_f32_e32 v60, 0xbfb8aa3b, v61
	v_exp_f32_e32 v62, v62
	v_exp_f32_e32 v63, v63
	v_exp_f32_e32 v57, v57
	v_mul_f32_e32 v58, 0xbfb8aa3b, v59
	v_exp_f32_e32 v65, v60
	v_exp_f32_e32 v58, v58
	v_add_f32_e32 v62, 1.0, v62
	v_add_f32_e32 v63, 1.0, v63
	v_rcp_f32_e32 v59, v56
	v_add_f32_e32 v56, 1.0, v57
	v_add_f32_e32 v64, 1.0, v64
	v_add_f32_e32 v65, 1.0, v65
	v_rcp_f32_e32 v62, v62
	v_rcp_f32_e32 v63, v63
	v_rcp_f32_e32 v67, v56
	v_add_f32_e32 v56, 1.0, v58
	v_mul_f32_e32 v48, 0xbfb8aa3b, v48
	v_rcp_f32_e32 v64, v64
	v_rcp_f32_e32 v65, v65
	v_rcp_f32_e32 v68, v56
	v_exp_f32_e32 v48, v48
	v_mul_f32_e32 v49, 0xbfb8aa3b, v49
	v_exp_f32_e32 v49, v49
	s_mov_b32 s1, 0x40000
	v_cvt_pk_bf16_f32 v57, v62, v63
	v_add_co_u32_e32 v62, vcc, s1, v124
	v_cvt_pk_bf16_f32 v56, v64, v65
	v_cvt_pk_bf16_f32 v58, v66, v59
	v_cvt_pk_bf16_f32 v59, v67, v68
	v_addc_co_u32_e32 v63, vcc, 0, v125, vcc
	v_add_f32_e32 v48, 1.0, v48
	global_store_dwordx4 v[62:63], v[56:59], off nt
	v_mul_f32_e32 v52, 0xbfb8aa3b, v52
	v_mul_f32_e32 v53, 0xbfb8aa3b, v53
	v_rcp_f32_e32 v56, v48
	v_add_f32_e32 v48, 1.0, v49
	v_mul_f32_e32 v49, 0xbfb8aa3b, v50
	v_mul_f32_e32 v54, 0xbfb8aa3b, v54
	v_mul_f32_e32 v55, 0xbfb8aa3b, v55
	v_exp_f32_e32 v49, v49
	v_mul_f32_e32 v50, 0xbfb8aa3b, v51
	v_exp_f32_e32 v52, v52
	v_exp_f32_e32 v53, v53
	v_exp_f32_e32 v54, v54
	v_exp_f32_e32 v55, v55
	v_exp_f32_e32 v50, v50
	v_rcp_f32_e32 v51, v48
	v_add_f32_e32 v48, 1.0, v49
	v_add_f32_e32 v52, 1.0, v52
	v_add_f32_e32 v53, 1.0, v53
	v_add_f32_e32 v54, 1.0, v54
	v_add_f32_e32 v55, 1.0, v55
	v_rcp_f32_e32 v57, v48
	v_add_f32_e32 v48, 1.0, v50
	v_mul_f32_e32 v40, 0xbfb8aa3b, v40
	v_rcp_f32_e32 v52, v52
	v_rcp_f32_e32 v53, v53
	v_rcp_f32_e32 v54, v54
	v_rcp_f32_e32 v55, v55
	v_rcp_f32_e32 v58, v48
	v_exp_f32_e32 v40, v40
	v_mul_f32_e32 v41, 0xbfb8aa3b, v41
	v_exp_f32_e32 v41, v41
	s_mov_b64 s[14:15], 0x40000
	v_lshl_add_u64 v[60:61], v[124:125], 0, s[14:15]
	v_cvt_pk_bf16_f32 v48, v52, v53
	v_cvt_pk_bf16_f32 v49, v54, v55
	v_cvt_pk_bf16_f32 v50, v56, v51
	v_cvt_pk_bf16_f32 v51, v57, v58
	v_add_f32_e32 v40, 1.0, v40
	global_store_dwordx4 v[60:61], v[48:51], off offset:256 nt
	v_mul_f32_e32 v44, 0xbfb8aa3b, v44
	v_mul_f32_e32 v46, 0xbfb8aa3b, v46
	v_mul_f32_e32 v47, 0xbfb8aa3b, v47
	v_rcp_f32_e32 v50, v40
	v_add_f32_e32 v40, 1.0, v41
	v_mul_f32_e32 v41, 0xbfb8aa3b, v42
	v_exp_f32_e32 v48, v44
	v_mul_f32_e32 v44, 0xbfb8aa3b, v45
	v_exp_f32_e32 v46, v46
	v_exp_f32_e32 v47, v47
	v_exp_f32_e32 v41, v41
	v_mul_f32_e32 v42, 0xbfb8aa3b, v43
	v_exp_f32_e32 v49, v44
	v_exp_f32_e32 v42, v42
	v_add_f32_e32 v46, 1.0, v46
	v_add_f32_e32 v47, 1.0, v47
	v_rcp_f32_e32 v43, v40
	v_add_f32_e32 v40, 1.0, v41
	v_add_f32_e32 v48, 1.0, v48
	v_add_f32_e32 v49, 1.0, v49
	v_rcp_f32_e32 v46, v46
	v_rcp_f32_e32 v47, v47
	v_rcp_f32_e32 v51, v40
	v_add_f32_e32 v40, 1.0, v42
	v_mul_f32_e32 v32, 0xbfb8aa3b, v32
	v_rcp_f32_e32 v48, v48
	v_rcp_f32_e32 v49, v49
	v_rcp_f32_e32 v52, v40
	v_exp_f32_e32 v32, v32
	v_mul_f32_e32 v33, 0xbfb8aa3b, v33
	v_exp_f32_e32 v33, v33
	s_mov_b32 s1, 0x48000
	v_cvt_pk_bf16_f32 v41, v46, v47
	v_add_co_u32_e32 v46, vcc, s1, v124
	v_cvt_pk_bf16_f32 v40, v48, v49
	v_cvt_pk_bf16_f32 v42, v50, v43
	v_cvt_pk_bf16_f32 v43, v51, v52
	v_addc_co_u32_e32 v47, vcc, 0, v125, vcc
	v_add_f32_e32 v32, 1.0, v32
	global_store_dwordx4 v[46:47], v[40:43], off nt
	v_mul_f32_e32 v36, 0xbfb8aa3b, v36
	v_mul_f32_e32 v37, 0xbfb8aa3b, v37
	v_rcp_f32_e32 v40, v32
	v_add_f32_e32 v32, 1.0, v33
	v_mul_f32_e32 v33, 0xbfb8aa3b, v34
	v_mul_f32_e32 v38, 0xbfb8aa3b, v38
	v_mul_f32_e32 v39, 0xbfb8aa3b, v39
	v_exp_f32_e32 v33, v33
	v_mul_f32_e32 v34, 0xbfb8aa3b, v35
	v_exp_f32_e32 v36, v36
	v_exp_f32_e32 v37, v37
	v_exp_f32_e32 v38, v38
	v_exp_f32_e32 v39, v39
	v_exp_f32_e32 v34, v34
	v_rcp_f32_e32 v35, v32
	v_add_f32_e32 v32, 1.0, v33
	v_add_f32_e32 v36, 1.0, v36
	v_add_f32_e32 v37, 1.0, v37
	v_add_f32_e32 v38, 1.0, v38
	v_add_f32_e32 v39, 1.0, v39
	v_rcp_f32_e32 v41, v32
	v_add_f32_e32 v32, 1.0, v34
	v_mul_f32_e32 v24, 0xbfb8aa3b, v24
	v_rcp_f32_e32 v36, v36
	v_rcp_f32_e32 v37, v37
	v_rcp_f32_e32 v38, v38
	v_rcp_f32_e32 v39, v39
	v_rcp_f32_e32 v42, v32
	v_exp_f32_e32 v24, v24
	v_mul_f32_e32 v25, 0xbfb8aa3b, v25
	v_exp_f32_e32 v25, v25
	s_mov_b64 s[14:15], 0x48000
	v_lshl_add_u64 v[44:45], v[124:125], 0, s[14:15]
	v_cvt_pk_bf16_f32 v32, v36, v37
	v_cvt_pk_bf16_f32 v33, v38, v39
	v_cvt_pk_bf16_f32 v34, v40, v35
	v_cvt_pk_bf16_f32 v35, v41, v42
	v_add_f32_e32 v24, 1.0, v24
	global_store_dwordx4 v[44:45], v[32:35], off offset:256 nt
	v_mul_f32_e32 v28, 0xbfb8aa3b, v28
	v_mul_f32_e32 v30, 0xbfb8aa3b, v30
	v_mul_f32_e32 v31, 0xbfb8aa3b, v31
	v_rcp_f32_e32 v34, v24
	v_add_f32_e32 v24, 1.0, v25
	v_mul_f32_e32 v25, 0xbfb8aa3b, v26
	v_exp_f32_e32 v32, v28
	v_mul_f32_e32 v28, 0xbfb8aa3b, v29
	v_exp_f32_e32 v30, v30
	v_exp_f32_e32 v31, v31
	v_exp_f32_e32 v25, v25
	v_mul_f32_e32 v26, 0xbfb8aa3b, v27
	v_exp_f32_e32 v33, v28
	v_exp_f32_e32 v26, v26
	v_add_f32_e32 v30, 1.0, v30
	v_add_f32_e32 v31, 1.0, v31
	v_rcp_f32_e32 v27, v24
	v_add_f32_e32 v24, 1.0, v25
	v_add_f32_e32 v32, 1.0, v32
	v_add_f32_e32 v33, 1.0, v33
	v_rcp_f32_e32 v30, v30
	v_rcp_f32_e32 v31, v31
	v_rcp_f32_e32 v35, v24
	v_add_f32_e32 v24, 1.0, v26
	v_mul_f32_e32 v16, 0xbfb8aa3b, v16
	v_rcp_f32_e32 v32, v32
	v_rcp_f32_e32 v33, v33
	v_rcp_f32_e32 v36, v24
	v_exp_f32_e32 v16, v16
	v_mul_f32_e32 v17, 0xbfb8aa3b, v17
	v_exp_f32_e32 v17, v17
	s_mov_b32 s1, 0x50000
	v_cvt_pk_bf16_f32 v25, v30, v31
	v_add_co_u32_e32 v30, vcc, s1, v124
	v_cvt_pk_bf16_f32 v24, v32, v33
	v_cvt_pk_bf16_f32 v26, v34, v27
	v_cvt_pk_bf16_f32 v27, v35, v36
	v_addc_co_u32_e32 v31, vcc, 0, v125, vcc
	v_add_f32_e32 v16, 1.0, v16
	global_store_dwordx4 v[30:31], v[24:27], off nt
	v_mul_f32_e32 v20, 0xbfb8aa3b, v20
	v_mul_f32_e32 v21, 0xbfb8aa3b, v21
	v_rcp_f32_e32 v24, v16
	v_add_f32_e32 v16, 1.0, v17
	v_mul_f32_e32 v17, 0xbfb8aa3b, v18
	v_mul_f32_e32 v22, 0xbfb8aa3b, v22
	v_mul_f32_e32 v23, 0xbfb8aa3b, v23
	v_exp_f32_e32 v17, v17
	v_mul_f32_e32 v18, 0xbfb8aa3b, v19
	v_exp_f32_e32 v20, v20
	v_exp_f32_e32 v21, v21
	v_exp_f32_e32 v22, v22
	v_exp_f32_e32 v23, v23
	v_exp_f32_e32 v18, v18
	v_rcp_f32_e32 v19, v16
	v_add_f32_e32 v16, 1.0, v17
	v_add_f32_e32 v20, 1.0, v20
	v_add_f32_e32 v21, 1.0, v21
	v_add_f32_e32 v22, 1.0, v22
	v_add_f32_e32 v23, 1.0, v23
	v_rcp_f32_e32 v25, v16
	v_add_f32_e32 v16, 1.0, v18
	v_mul_f32_e32 v8, 0xbfb8aa3b, v8
	v_rcp_f32_e32 v20, v20
	v_rcp_f32_e32 v21, v21
	v_rcp_f32_e32 v22, v22
	v_rcp_f32_e32 v23, v23
	v_rcp_f32_e32 v26, v16
	v_exp_f32_e32 v8, v8
	v_mul_f32_e32 v9, 0xbfb8aa3b, v9
	v_exp_f32_e32 v9, v9
	s_mov_b64 s[14:15], 0x50000
	v_lshl_add_u64 v[28:29], v[124:125], 0, s[14:15]
	v_cvt_pk_bf16_f32 v16, v20, v21
	v_cvt_pk_bf16_f32 v17, v22, v23
	v_cvt_pk_bf16_f32 v18, v24, v19
	v_cvt_pk_bf16_f32 v19, v25, v26
	v_add_f32_e32 v8, 1.0, v8
	global_store_dwordx4 v[28:29], v[16:19], off offset:256 nt
	v_mul_f32_e32 v12, 0xbfb8aa3b, v12
	v_mul_f32_e32 v14, 0xbfb8aa3b, v14
	v_mul_f32_e32 v15, 0xbfb8aa3b, v15
	v_rcp_f32_e32 v18, v8
	v_add_f32_e32 v8, 1.0, v9
	v_mul_f32_e32 v9, 0xbfb8aa3b, v10
	v_exp_f32_e32 v16, v12
	v_mul_f32_e32 v12, 0xbfb8aa3b, v13
	v_exp_f32_e32 v14, v14
	v_exp_f32_e32 v15, v15
	v_exp_f32_e32 v9, v9
	v_mul_f32_e32 v10, 0xbfb8aa3b, v11
	v_exp_f32_e32 v17, v12
	v_exp_f32_e32 v10, v10
	v_add_f32_e32 v14, 1.0, v14
	v_add_f32_e32 v15, 1.0, v15
	v_rcp_f32_e32 v11, v8
	v_add_f32_e32 v8, 1.0, v9
	v_add_f32_e32 v16, 1.0, v16
	v_add_f32_e32 v17, 1.0, v17
	v_rcp_f32_e32 v14, v14
	v_rcp_f32_e32 v15, v15
	v_rcp_f32_e32 v19, v8
	v_add_f32_e32 v8, 1.0, v10
	v_mul_f32_e32 v0, 0xbfb8aa3b, v0
	v_rcp_f32_e32 v16, v16
	v_rcp_f32_e32 v17, v17
	v_rcp_f32_e32 v20, v8
	v_exp_f32_e32 v0, v0
	v_mul_f32_e32 v1, 0xbfb8aa3b, v1
	v_exp_f32_e32 v1, v1
	s_mov_b32 s1, 0x58000
	v_cvt_pk_bf16_f32 v9, v14, v15
	v_add_co_u32_e32 v14, vcc, s1, v124
	v_cvt_pk_bf16_f32 v8, v16, v17
	v_cvt_pk_bf16_f32 v10, v18, v11
	v_cvt_pk_bf16_f32 v11, v19, v20
	v_addc_co_u32_e32 v15, vcc, 0, v125, vcc
	v_add_f32_e32 v0, 1.0, v0
	global_store_dwordx4 v[14:15], v[8:11], off nt
	v_mul_f32_e32 v4, 0xbfb8aa3b, v4
	v_mul_f32_e32 v5, 0xbfb8aa3b, v5
	v_rcp_f32_e32 v8, v0
	v_add_f32_e32 v0, 1.0, v1
	v_mul_f32_e32 v1, 0xbfb8aa3b, v2
	v_mul_f32_e32 v6, 0xbfb8aa3b, v6
	v_mul_f32_e32 v7, 0xbfb8aa3b, v7
	v_exp_f32_e32 v1, v1
	v_mul_f32_e32 v2, 0xbfb8aa3b, v3
	v_exp_f32_e32 v4, v4
	v_exp_f32_e32 v5, v5
	v_exp_f32_e32 v6, v6
	v_exp_f32_e32 v7, v7
	v_exp_f32_e32 v2, v2
	v_rcp_f32_e32 v3, v0
	v_add_f32_e32 v0, 1.0, v1
	v_add_f32_e32 v4, 1.0, v4
	v_add_f32_e32 v5, 1.0, v5
	v_add_f32_e32 v6, 1.0, v6
	v_add_f32_e32 v7, 1.0, v7
	v_rcp_f32_e32 v9, v0
	v_add_f32_e32 v0, 1.0, v2
	v_rcp_f32_e32 v4, v4
	v_rcp_f32_e32 v5, v5
	v_rcp_f32_e32 v6, v6
	v_rcp_f32_e32 v7, v7
	v_rcp_f32_e32 v10, v0
	s_mov_b64 s[14:15], 0x58000
	v_lshl_add_u64 v[12:13], v[124:125], 0, s[14:15]
	v_cvt_pk_bf16_f32 v0, v4, v5
	v_cvt_pk_bf16_f32 v1, v6, v7
	v_cvt_pk_bf16_f32 v2, v8, v3
	v_cvt_pk_bf16_f32 v3, v9, v10
	s_andn2_b64 vcc, exec, s[6:7]
	s_mov_b64 s[6:7], -1
	global_store_dwordx4 v[12:13], v[0:3], off offset:256 nt
	s_cbranch_vccnz .LBB0_459
	s_and_b64 vcc, exec, s[4:5]
	s_cbranch_vccnz .LBB0_458
	s_barrier
	s_branch .LBB0_458
